# GEMM K loops (P1, P4, parts of P3/P5/P6): k-halves of each accumulator issued back to back (accumulate chain), staged lgkmcnt waits dropped
# speedup vs baseline: 1.0069x; 1.0069x over previous
; #define PG8_STAGE(bufoff, gbase, voff) do { if constexpr (ABL & 1) break; glds16s<(bufoff)>((voff)[0], (const void*)(gbase), ldsbw); glds16s<(bufoff) + 8192>((voff)[1], (const void*)(gbase), ldsbw); } while (0)
; #define PG8_LDA(dst, b, h) do { if constexpr (ABL & 4) break; _Pragma("unroll") for (int m = 0; m < 4; ++m) _Pragma("unroll") for (int k = 0; k < 2; ++k) dst[m][k] = *(const LAS f16x8*)(lds + PG8_SA(b, h) + aoff + m * 2048 + k * 1024); } while (0)
; #define PG8_LDB(dst, b, h) do { if constexpr (ABL & 4) break; _Pragma("unroll") for (int n = 0; n < 2; ++n) _Pragma("unroll") for (int k = 0; k < 2; ++k) dst[n][k] = *(const LAS f16x8*)(lds + PG8_SB(b, h) + boff + n * 2048 + k * 1024); } while (0)
; #define PG8_MMA(ai, bj, At, Bt) do { if constexpr (ABL & 2) break; __builtin_amdgcn_s_setprio(1); _Pragma("unroll") for (int m = 0; m < 4; ++m) _Pragma("unroll") for (int n = 0; n < 2; ++n) _Pragma("unroll") for (int k = 0; k < 2; ++k) \
;         acc[ai][bj][m][n] = __builtin_amdgcn_mfma_f32_16x16x32_f16(Bt[n][k], At[m][k], acc[ai][bj][m][n], 0, 0, 0); __builtin_amdgcn_s_setprio(0); } while (0)
; #define PG8_WAIT_V(n) asm volatile("s_waitcnt vmcnt(" #n ")" ::: "memory")
;     ...
;             PG8_LDB(B0, 0, 0); PG8_LDB(B1, 0, 1); PG8_SCHED; PG8_LDA(At, 0, 0); PG8_STAGE(PG8_SA(1, 1), a1 + hstep, voffA);
;             PG8_WAIT_V(8); PG8_WAIT_L(0); PG8_BAR; PG8_MMAF(0, 0, At, B0); PG8_MMAF(0, 1, At, B1); PG8_BAR; PG8_SCHED;
;             const bool fin = last && !has_next;
;             PG8_LDA(At, 0, 1); if (!fin) { PG8_STAGE(PG8_SB(0, 0), b2, voffB); PG8_STAGE(PG8_SB(0, 1), b2 + hstep, voffB); PG8_STAGE(PG8_SA(0, 0), a2, voffA); }
;             if (!fin) PG8_WAIT_V(8); else PG8_WAIT_V(2); PG8_WAIT_L(0); PG8_BAR; PG8_MMAF(1, 0, At, B0); PG8_MMAF(1, 1, At, B1); PG8_BAR; PG8_SCHED;
;             PG8_LDB(B0, 1, 0); PG8_LDB(B1, 1, 1); PG8_SCHED; PG8_LDA(At, 1, 0); if (!fin) PG8_STAGE(PG8_SA(0, 1), a2 + hstep, voffA);
;             if (!fin) PG8_WAIT_V(8); else PG8_WAIT_V(0); PG8_WAIT_L(0); PG8_BAR; PG8_MMA(0, 0, At, B0); PG8_MMA(0, 1, At, B1); PG8_BAR; PG8_SCHED;
;             PG8_LDA(At, 1, 1); if (!fin) { PG8_STAGE(PG8_SB(1, 0), b3, voffB); PG8_STAGE(PG8_SB(1, 1), b3 + hstep, voffB); PG8_STAGE(PG8_SA(1, 0), a3, voffA); }
;             if (!fin) PG8_WAIT_V(8); PG8_WAIT_L(0); PG8_BAR; PG8_MMA(1, 0, At, B0); PG8_MMA(1, 1, At, B1); PG8_BAR; PG8_SCHED;
.LBB0_230:
	s_waitcnt lgkmcnt(0)
	s_barrier
	v_mfma_f32_16x16x32_f16 v[54:57], v[154:157], v[186:189], v[54:57]
	s_setprio 1
	v_mfma_f32_16x16x32_f16 v[54:57], v[158:161], v[190:193], v[54:57]
	v_mfma_f32_16x16x32_f16 v[46:49], v[146:149], v[186:189], v[46:49]
	v_mfma_f32_16x16x32_f16 v[46:49], v[150:153], v[190:193], v[46:49]
	v_mfma_f32_16x16x32_f16 v[34:37], v[154:157], v[178:181], v[34:37]
	v_mfma_f32_16x16x32_f16 v[34:37], v[158:161], v[182:185], v[34:37]
	v_mfma_f32_16x16x32_f16 v[30:33], v[146:149], v[178:181], v[30:33]
	v_mfma_f32_16x16x32_f16 v[30:33], v[150:153], v[182:185], v[30:33]
	v_mfma_f32_16x16x32_f16 v[18:21], v[154:157], v[170:173], v[18:21]
	v_mfma_f32_16x16x32_f16 v[18:21], v[158:161], v[174:177], v[18:21]
	v_mfma_f32_16x16x32_f16 v[14:17], v[146:149], v[170:173], v[14:17]
	v_mfma_f32_16x16x32_f16 v[14:17], v[150:153], v[174:177], v[14:17]
	v_mfma_f32_16x16x32_f16 v[6:9], v[154:157], v[162:165], v[6:9]
	v_mfma_f32_16x16x32_f16 v[6:9], v[158:161], v[166:169], v[6:9]
	v_mfma_f32_16x16x32_f16 v[2:5], v[146:149], v[162:165], v[2:5]
	v_mfma_f32_16x16x32_f16 v[2:5], v[150:153], v[166:169], v[2:5]
	v_mfma_f32_16x16x32_f16 v[82:85], v[138:141], v[186:189], v[82:85]
	v_mfma_f32_16x16x32_f16 v[82:85], v[142:145], v[190:193], v[82:85]
	v_mfma_f32_16x16x32_f16 v[70:73], v[130:133], v[186:189], v[70:73]
	v_mfma_f32_16x16x32_f16 v[70:73], v[134:137], v[190:193], v[70:73]
	v_mfma_f32_16x16x32_f16 v[62:65], v[138:141], v[178:181], v[62:65]
	v_mfma_f32_16x16x32_f16 v[62:65], v[142:145], v[182:185], v[62:65]
	v_mfma_f32_16x16x32_f16 v[42:45], v[130:133], v[178:181], v[42:45]
	v_mfma_f32_16x16x32_f16 v[42:45], v[134:137], v[182:185], v[42:45]
	v_mfma_f32_16x16x32_f16 v[38:41], v[138:141], v[170:173], v[38:41]
	v_mfma_f32_16x16x32_f16 v[38:41], v[142:145], v[174:177], v[38:41]
	v_mfma_f32_16x16x32_f16 v[26:29], v[130:133], v[170:173], v[26:29]
	v_mfma_f32_16x16x32_f16 v[26:29], v[134:137], v[174:177], v[26:29]
	v_mfma_f32_16x16x32_f16 v[22:25], v[138:141], v[162:165], v[22:25]
	v_mfma_f32_16x16x32_f16 v[22:25], v[142:145], v[166:169], v[22:25]
	v_mfma_f32_16x16x32_f16 v[10:13], v[130:133], v[162:165], v[10:13]
	v_mfma_f32_16x16x32_f16 v[10:13], v[134:137], v[166:169], v[10:13]
	s_barrier
	s_setprio 0
	s_add_i32 s64, s64, 2
	s_add_u32 s53, s53, 0x100
	s_addc_u32 s61, s61, 0
	s_cmp_gt_u32 s64, 13
	s_cbranch_scc1 .LBB0_241
.LBB0_231:
	ds_read_b128 v[146:149], v236
	ds_read_b128 v[150:153], v236 offset:1024
	ds_read_b128 v[154:157], v236 offset:2048
	ds_read_b128 v[158:161], v236 offset:3072
	ds_read_b128 v[130:133], v237
	ds_read_b128 v[134:137], v237 offset:1024
	ds_read_b128 v[138:141], v237 offset:2048
	ds_read_b128 v[142:145], v237 offset:3072
	s_mov_b64 s[6:7], s[8:9]
	s_add_u32 s8, s6, 0x100
	s_addc_u32 s9, s7, 0
	s_cmp_eq_u32 s64, 12
	s_cselect_b64 s[62:63], -1, 0
	s_and_b64 s[24:25], s[62:63], exec
	s_cselect_b32 s27, s11, s9
	s_cselect_b32 s26, s35, s8
	s_cselect_b32 s25, s1, s61
	s_cselect_b32 s24, s46, s53
	ds_read_b128 v[162:165], v238
	ds_read_b128 v[166:169], v238 offset:1024
	ds_read_b128 v[170:173], v238 offset:2048
	ds_read_b128 v[174:177], v238 offset:3072
	ds_read_b128 v[178:181], v238 offset:4096
	ds_read_b128 v[182:185], v238 offset:5120
	ds_read_b128 v[186:189], v238 offset:6144
	ds_read_b128 v[190:193], v238 offset:7168
	s_add_u32 s6, s6, 0x40080
	s_addc_u32 s7, s7, 0
	s_add_u32 m0, s28, 0xc000
	s_nop 0
	global_load_lds_dwordx4 v232, s[6:7]
	s_nop 0
	s_add_u32 m0, s28, 0xe000
	s_nop 0
	global_load_lds_dwordx4 v234, s[6:7]
	s_waitcnt vmcnt(8)
	s_waitcnt lgkmcnt(0)
	s_barrier
	v_mfma_f32_16x16x32_f16 v[118:121], v[146:149], v[162:165], v[118:121]
	s_setprio 1
	v_mfma_f32_16x16x32_f16 v[118:121], v[150:153], v[166:169], v[118:121]
	v_mfma_f32_16x16x32_f16 v[114:117], v[154:157], v[162:165], v[114:117]
	v_mfma_f32_16x16x32_f16 v[114:117], v[158:161], v[166:169], v[114:117]
	v_mfma_f32_16x16x32_f16 v[102:105], v[146:149], v[170:173], v[102:105]
	v_mfma_f32_16x16x32_f16 v[102:105], v[150:153], v[174:177], v[102:105]
	v_mfma_f32_16x16x32_f16 v[98:101], v[154:157], v[170:173], v[98:101]
	v_mfma_f32_16x16x32_f16 v[98:101], v[158:161], v[174:177], v[98:101]
	v_mfma_f32_16x16x32_f16 v[86:89], v[146:149], v[178:181], v[86:89]
	v_mfma_f32_16x16x32_f16 v[86:89], v[150:153], v[182:185], v[86:89]
	v_mfma_f32_16x16x32_f16 v[78:81], v[154:157], v[178:181], v[78:81]
	v_mfma_f32_16x16x32_f16 v[78:81], v[158:161], v[182:185], v[78:81]
	v_mfma_f32_16x16x32_f16 v[58:61], v[146:149], v[186:189], v[58:61]
	v_mfma_f32_16x16x32_f16 v[58:61], v[150:153], v[190:193], v[58:61]
	v_mfma_f32_16x16x32_f16 v[50:53], v[154:157], v[186:189], v[50:53]
	v_mfma_f32_16x16x32_f16 v[50:53], v[158:161], v[190:193], v[50:53]
	v_mfma_f32_16x16x32_f16 v[126:129], v[130:133], v[162:165], v[126:129]
	v_mfma_f32_16x16x32_f16 v[126:129], v[134:137], v[166:169], v[126:129]
	v_mfma_f32_16x16x32_f16 v[122:125], v[138:141], v[162:165], v[122:125]
	v_mfma_f32_16x16x32_f16 v[122:125], v[142:145], v[166:169], v[122:125]
	v_mfma_f32_16x16x32_f16 v[110:113], v[130:133], v[170:173], v[110:113]
	v_mfma_f32_16x16x32_f16 v[110:113], v[134:137], v[174:177], v[110:113]
	v_mfma_f32_16x16x32_f16 v[106:109], v[138:141], v[170:173], v[106:109]
	v_mfma_f32_16x16x32_f16 v[106:109], v[142:145], v[174:177], v[106:109]
	v_mfma_f32_16x16x32_f16 v[94:97], v[130:133], v[178:181], v[94:97]
	v_mfma_f32_16x16x32_f16 v[94:97], v[134:137], v[182:185], v[94:97]
	v_mfma_f32_16x16x32_f16 v[90:93], v[138:141], v[178:181], v[90:93]
	v_mfma_f32_16x16x32_f16 v[90:93], v[142:145], v[182:185], v[90:93]
	v_mfma_f32_16x16x32_f16 v[74:77], v[130:133], v[186:189], v[74:77]
	v_mfma_f32_16x16x32_f16 v[74:77], v[134:137], v[190:193], v[74:77]
	v_mfma_f32_16x16x32_f16 v[66:69], v[138:141], v[186:189], v[66:69]
	v_mfma_f32_16x16x32_f16 v[66:69], v[142:145], v[190:193], v[66:69]
	s_barrier
	s_setprio 0
	ds_read_b128 v[186:189], v238 offset:16384
	ds_read_b128 v[190:193], v238 offset:17408
	ds_read_b128 v[178:181], v238 offset:18432
	ds_read_b128 v[182:185], v238 offset:19456
	ds_read_b128 v[170:173], v238 offset:20480
	ds_read_b128 v[174:177], v238 offset:21504
	ds_read_b128 v[162:165], v238 offset:22528
	ds_read_b128 v[166:169], v238 offset:23552
	s_and_b64 s[6:7], s[4:5], s[62:63]
	s_mov_b64 s[62:63], -1
	s_and_b64 vcc, exec, s[6:7]
	s_cbranch_vccnz .LBB0_233
	s_add_u32 m0, s28, 0x10000
	s_nop 0
	global_load_lds_dwordx4 v233, s[24:25]
	s_nop 0
	s_add_u32 m0, s28, 0x12000
	s_nop 0
	global_load_lds_dwordx4 v235, s[24:25]
	s_add_u32 s62, s24, 0x40000
	s_addc_u32 s63, s25, 0
	s_add_u32 m0, s28, 0x14000
	s_nop 0
	global_load_lds_dwordx4 v233, s[62:63]
	s_nop 0
	s_add_u32 m0, s28, 0x16000
	s_nop 0
	global_load_lds_dwordx4 v235, s[62:63]
	s_mov_b64 s[62:63], 0
	s_add_u32 m0, s28, 0
	s_nop 0
	global_load_lds_dwordx4 v232, s[26:27]
	s_nop 0
	s_add_u32 m0, s28, 0x2000
	s_nop 0
	global_load_lds_dwordx4 v234, s[26:27]
	s_waitcnt vmcnt(8)

; #define PG8_STAGE(bufoff, gbase, voff) do { if constexpr (ABL & 1) break; glds16s<(bufoff)>((voff)[0], (const void*)(gbase), ldsbw); glds16s<(bufoff) + 8192>((voff)[1], (const void*)(gbase), ldsbw); } while (0)
; #define PG8_LDA(dst, b, h) do { if constexpr (ABL & 4) break; _Pragma("unroll") for (int m = 0; m < 4; ++m) _Pragma("unroll") for (int k = 0; k < 2; ++k) dst[m][k] = *(const LAS f16x8*)(lds + PG8_SA(b, h) + aoff + m * 2048 + k * 1024); } while (0)
; #define PG8_LDB(dst, b, h) do { if constexpr (ABL & 4) break; _Pragma("unroll") for (int n = 0; n < 2; ++n) _Pragma("unroll") for (int k = 0; k < 2; ++k) dst[n][k] = *(const LAS f16x8*)(lds + PG8_SB(b, h) + boff + n * 2048 + k * 1024); } while (0)
; #define PG8_MMA(ai, bj, At, Bt) do { if constexpr (ABL & 2) break; __builtin_amdgcn_s_setprio(1); _Pragma("unroll") for (int m = 0; m < 4; ++m) _Pragma("unroll") for (int n = 0; n < 2; ++n) _Pragma("unroll") for (int k = 0; k < 2; ++k) \
;         acc[ai][bj][m][n] = __builtin_amdgcn_mfma_f32_16x16x32_f16(Bt[n][k], At[m][k], acc[ai][bj][m][n], 0, 0, 0); __builtin_amdgcn_s_setprio(0); } while (0)
; #define PG8_MMAF(ai, bj, At, Bt) do { if (t == 0) PG8_MMA0(ai, bj, At, Bt); else PG8_MMA(ai, bj, At, Bt); } while (0)
; #define PG8_WAIT_V(n) asm volatile("s_waitcnt vmcnt(" #n ")" ::: "memory")
; #define PG8_WAIT_L(n) asm volatile("s_waitcnt lgkmcnt(" #n ")" ::: "memory")
; #define PG8_BAR __builtin_amdgcn_s_barrier()
; #define PG8_SCHED __builtin_amdgcn_sched_barrier(0)
;     ...
;             if (!fin) PG8_WAIT_V(8); else PG8_WAIT_V(2); PG8_WAIT_L(0); PG8_BAR; PG8_MMAF(1, 0, At, B0); PG8_MMAF(1, 1, At, B1); PG8_BAR; PG8_SCHED;
;             PG8_LDB(B0, 1, 0); PG8_LDB(B1, 1, 1); PG8_SCHED; PG8_LDA(At, 1, 0); if (!fin) PG8_STAGE(PG8_SA(0, 1), a2 + hstep, voffA);
;             if (!fin) PG8_WAIT_V(8); else PG8_WAIT_V(0); PG8_WAIT_L(0); PG8_BAR; PG8_MMA(0, 0, At, B0); PG8_MMA(0, 1, At, B1); PG8_BAR; PG8_SCHED;
.LBB0_235:
	s_waitcnt lgkmcnt(0)
	s_xor_b64 s[62:63], s[6:7], -1
	s_barrier
	v_mfma_f32_16x16x32_f16 v[54:57], v[146:149], v[186:189], v[54:57]
	s_setprio 1
	v_mfma_f32_16x16x32_f16 v[54:57], v[150:153], v[190:193], v[54:57]
	v_mfma_f32_16x16x32_f16 v[46:49], v[154:157], v[186:189], v[46:49]
	v_mfma_f32_16x16x32_f16 v[46:49], v[158:161], v[190:193], v[46:49]
	v_mfma_f32_16x16x32_f16 v[34:37], v[146:149], v[178:181], v[34:37]
	v_mfma_f32_16x16x32_f16 v[34:37], v[150:153], v[182:185], v[34:37]
	v_mfma_f32_16x16x32_f16 v[30:33], v[154:157], v[178:181], v[30:33]
	v_mfma_f32_16x16x32_f16 v[30:33], v[158:161], v[182:185], v[30:33]
	v_mfma_f32_16x16x32_f16 v[18:21], v[146:149], v[170:173], v[18:21]
	v_mfma_f32_16x16x32_f16 v[18:21], v[150:153], v[174:177], v[18:21]
	v_mfma_f32_16x16x32_f16 v[14:17], v[154:157], v[170:173], v[14:17]
	v_mfma_f32_16x16x32_f16 v[14:17], v[158:161], v[174:177], v[14:17]
	v_mfma_f32_16x16x32_f16 v[6:9], v[146:149], v[162:165], v[6:9]
	v_mfma_f32_16x16x32_f16 v[6:9], v[150:153], v[166:169], v[6:9]
	v_mfma_f32_16x16x32_f16 v[2:5], v[154:157], v[162:165], v[2:5]
	v_mfma_f32_16x16x32_f16 v[2:5], v[158:161], v[166:169], v[2:5]
	v_mfma_f32_16x16x32_f16 v[82:85], v[130:133], v[186:189], v[82:85]
	v_mfma_f32_16x16x32_f16 v[82:85], v[134:137], v[190:193], v[82:85]
	v_mfma_f32_16x16x32_f16 v[70:73], v[138:141], v[186:189], v[70:73]
	v_mfma_f32_16x16x32_f16 v[70:73], v[142:145], v[190:193], v[70:73]
	v_mfma_f32_16x16x32_f16 v[62:65], v[130:133], v[178:181], v[62:65]
	v_mfma_f32_16x16x32_f16 v[62:65], v[134:137], v[182:185], v[62:65]
	v_mfma_f32_16x16x32_f16 v[42:45], v[138:141], v[178:181], v[42:45]
	v_mfma_f32_16x16x32_f16 v[42:45], v[142:145], v[182:185], v[42:45]
	v_mfma_f32_16x16x32_f16 v[38:41], v[130:133], v[170:173], v[38:41]
	v_mfma_f32_16x16x32_f16 v[38:41], v[134:137], v[174:177], v[38:41]
	v_mfma_f32_16x16x32_f16 v[26:29], v[138:141], v[170:173], v[26:29]
	v_mfma_f32_16x16x32_f16 v[26:29], v[142:145], v[174:177], v[26:29]
	v_mfma_f32_16x16x32_f16 v[22:25], v[130:133], v[162:165], v[22:25]
	v_mfma_f32_16x16x32_f16 v[22:25], v[134:137], v[166:169], v[22:25]
	v_mfma_f32_16x16x32_f16 v[10:13], v[138:141], v[162:165], v[10:13]
	v_mfma_f32_16x16x32_f16 v[10:13], v[142:145], v[166:169], v[10:13]
	s_barrier
	s_setprio 0
	ds_read_b128 v[154:157], v239
	ds_read_b128 v[158:161], v239 offset:1024
	ds_read_b128 v[146:149], v239 offset:2048
	ds_read_b128 v[150:153], v239 offset:3072
	ds_read_b128 v[138:141], v240
	ds_read_b128 v[142:145], v240 offset:1024
	ds_read_b128 v[130:133], v240 offset:2048
	ds_read_b128 v[134:137], v240 offset:3072
	ds_read_b128 v[186:189], v238 offset:32768
	ds_read_b128 v[190:193], v238 offset:33792
	ds_read_b128 v[178:181], v238 offset:34816
	ds_read_b128 v[182:185], v238 offset:35840
	ds_read_b128 v[170:173], v238 offset:36864
	ds_read_b128 v[174:177], v238 offset:37888
	ds_read_b128 v[162:165], v238 offset:38912
	ds_read_b128 v[166:169], v238 offset:39936
	v_cndmask_b32_e64 v198, 0, 1, s[62:63]
	v_cmp_ne_u32_e64 s[6:7], 1, v198
	s_andn2_b64 vcc, exec, s[62:63]
	s_mov_b64 s[62:63], -1
	s_cbranch_vccnz .LBB0_237
	s_add_u32 s62, s26, 0x40000
	s_addc_u32 s63, s27, 0
	s_add_u32 m0, s28, 0x4000
	s_nop 0
	global_load_lds_dwordx4 v232, s[62:63]
	s_nop 0
	s_add_u32 m0, s28, 0x6000
	s_nop 0
	global_load_lds_dwordx4 v234, s[62:63]
	s_waitcnt vmcnt(8)
	s_mov_b64 s[62:63], 0

; #define PG8_STAGE(bufoff, gbase, voff) do { if constexpr (ABL & 1) break; glds16s<(bufoff)>((voff)[0], (const void*)(gbase), ldsbw); glds16s<(bufoff) + 8192>((voff)[1], (const void*)(gbase), ldsbw); } while (0)
; #define PG8_LDA(dst, b, h) do { if constexpr (ABL & 4) break; _Pragma("unroll") for (int m = 0; m < 4; ++m) _Pragma("unroll") for (int k = 0; k < 2; ++k) dst[m][k] = *(const LAS f16x8*)(lds + PG8_SA(b, h) + aoff + m * 2048 + k * 1024); } while (0)
; #define PG8_MMA(ai, bj, At, Bt) do { if constexpr (ABL & 2) break; __builtin_amdgcn_s_setprio(1); _Pragma("unroll") for (int m = 0; m < 4; ++m) _Pragma("unroll") for (int n = 0; n < 2; ++n) _Pragma("unroll") for (int k = 0; k < 2; ++k) \
;         acc[ai][bj][m][n] = __builtin_amdgcn_mfma_f32_16x16x32_f16(Bt[n][k], At[m][k], acc[ai][bj][m][n], 0, 0, 0); __builtin_amdgcn_s_setprio(0); } while (0)
; #define PG8_WAIT_V(n) asm volatile("s_waitcnt vmcnt(" #n ")" ::: "memory")
; #define PG8_WAIT_L(n) asm volatile("s_waitcnt lgkmcnt(" #n ")" ::: "memory")
; #define PG8_BAR __builtin_amdgcn_s_barrier()
; #define PG8_SCHED __builtin_amdgcn_sched_barrier(0)
;     ...
;             if (!fin) PG8_WAIT_V(8); else PG8_WAIT_V(0); PG8_WAIT_L(0); PG8_BAR; PG8_MMA(0, 0, At, B0); PG8_MMA(0, 1, At, B1); PG8_BAR; PG8_SCHED;
;             PG8_LDA(At, 1, 1); if (!fin) { PG8_STAGE(PG8_SB(1, 0), b3, voffB); PG8_STAGE(PG8_SB(1, 1), b3 + hstep, voffB); PG8_STAGE(PG8_SA(1, 0), a3, voffA); }
;             if (!fin) PG8_WAIT_V(8); PG8_WAIT_L(0); PG8_BAR; PG8_MMA(1, 0, At, B0); PG8_MMA(1, 1, At, B1); PG8_BAR; PG8_SCHED;
.LBB0_239:
	s_waitcnt lgkmcnt(0)
	s_barrier
	v_mfma_f32_16x16x32_f16 v[118:121], v[154:157], v[186:189], v[118:121]
	s_setprio 1
	v_mfma_f32_16x16x32_f16 v[118:121], v[158:161], v[190:193], v[118:121]
	v_mfma_f32_16x16x32_f16 v[114:117], v[146:149], v[186:189], v[114:117]
	v_mfma_f32_16x16x32_f16 v[114:117], v[150:153], v[190:193], v[114:117]
	v_mfma_f32_16x16x32_f16 v[102:105], v[154:157], v[178:181], v[102:105]
	v_mfma_f32_16x16x32_f16 v[102:105], v[158:161], v[182:185], v[102:105]
	v_mfma_f32_16x16x32_f16 v[98:101], v[146:149], v[178:181], v[98:101]
	v_mfma_f32_16x16x32_f16 v[98:101], v[150:153], v[182:185], v[98:101]
	v_mfma_f32_16x16x32_f16 v[86:89], v[154:157], v[170:173], v[86:89]
	v_mfma_f32_16x16x32_f16 v[86:89], v[158:161], v[174:177], v[86:89]
	v_mfma_f32_16x16x32_f16 v[78:81], v[146:149], v[170:173], v[78:81]
	v_mfma_f32_16x16x32_f16 v[78:81], v[150:153], v[174:177], v[78:81]
	v_mfma_f32_16x16x32_f16 v[58:61], v[154:157], v[162:165], v[58:61]
	v_mfma_f32_16x16x32_f16 v[58:61], v[158:161], v[166:169], v[58:61]
	v_mfma_f32_16x16x32_f16 v[50:53], v[146:149], v[162:165], v[50:53]
	v_mfma_f32_16x16x32_f16 v[50:53], v[150:153], v[166:169], v[50:53]
	v_mfma_f32_16x16x32_f16 v[126:129], v[138:141], v[186:189], v[126:129]
	v_mfma_f32_16x16x32_f16 v[126:129], v[142:145], v[190:193], v[126:129]
	v_mfma_f32_16x16x32_f16 v[122:125], v[130:133], v[186:189], v[122:125]
	v_mfma_f32_16x16x32_f16 v[122:125], v[134:137], v[190:193], v[122:125]
	v_mfma_f32_16x16x32_f16 v[110:113], v[138:141], v[178:181], v[110:113]
	v_mfma_f32_16x16x32_f16 v[110:113], v[142:145], v[182:185], v[110:113]
	v_mfma_f32_16x16x32_f16 v[106:109], v[130:133], v[178:181], v[106:109]
	v_mfma_f32_16x16x32_f16 v[106:109], v[134:137], v[182:185], v[106:109]
	v_mfma_f32_16x16x32_f16 v[94:97], v[138:141], v[170:173], v[94:97]
	v_mfma_f32_16x16x32_f16 v[94:97], v[142:145], v[174:177], v[94:97]
	v_mfma_f32_16x16x32_f16 v[90:93], v[130:133], v[170:173], v[90:93]
	v_mfma_f32_16x16x32_f16 v[90:93], v[134:137], v[174:177], v[90:93]
	v_mfma_f32_16x16x32_f16 v[74:77], v[138:141], v[162:165], v[74:77]
	v_mfma_f32_16x16x32_f16 v[74:77], v[142:145], v[166:169], v[74:77]
	v_mfma_f32_16x16x32_f16 v[66:69], v[130:133], v[162:165], v[66:69]
	v_mfma_f32_16x16x32_f16 v[66:69], v[134:137], v[166:169], v[66:69]
	s_barrier
	s_setprio 0
	ds_read_b128 v[186:189], v238 offset:49152
	ds_read_b128 v[190:193], v238 offset:50176
	ds_read_b128 v[178:181], v238 offset:51200
	ds_read_b128 v[182:185], v238 offset:52224
	ds_read_b128 v[170:173], v238 offset:53248
	ds_read_b128 v[174:177], v238 offset:54272
	ds_read_b128 v[162:165], v238 offset:55296
	ds_read_b128 v[166:169], v238 offset:56320
	s_and_b64 vcc, exec, s[6:7]
	s_cbranch_vccnz .LBB0_230
	s_add_u32 s6, s26, 0x80
	s_addc_u32 s7, s27, 0
	s_add_u32 s26, s24, 0x80
	s_addc_u32 s27, s25, 0
	s_add_u32 m0, s28, 0x18000
	s_nop 0
	global_load_lds_dwordx4 v233, s[26:27]
	s_nop 0
	s_add_u32 m0, s28, 0x1a000
	s_nop 0
	global_load_lds_dwordx4 v235, s[26:27]
	s_add_u32 s24, s24, 0x40080
	s_addc_u32 s25, s25, 0
	s_add_u32 m0, s28, 0x1c000
	s_nop 0
	global_load_lds_dwordx4 v233, s[24:25]
	s_nop 0
	s_add_u32 m0, s28, 0x1e000
	s_nop 0
	global_load_lds_dwordx4 v235, s[24:25]
	s_nop 0
	s_add_u32 m0, s28, 0x8000
	s_nop 0
	global_load_lds_dwordx4 v232, s[6:7]
	s_nop 0
	s_add_u32 m0, s28, 0xa000
	s_nop 0
	global_load_lds_dwordx4 v234, s[6:7]
	s_waitcnt vmcnt(8)
	s_branch .LBB0_230

; #define PG8_STAGE(bufoff, gbase, voff) do { if constexpr (ABL & 1) break; glds16s<(bufoff)>((voff)[0], (const void*)(gbase), ldsbw); glds16s<(bufoff) + 8192>((voff)[1], (const void*)(gbase), ldsbw); } while (0)
; #define PG8_LDA(dst, b, h) do { if constexpr (ABL & 4) break; _Pragma("unroll") for (int m = 0; m < 4; ++m) _Pragma("unroll") for (int k = 0; k < 2; ++k) dst[m][k] = *(const LAS f16x8*)(lds + PG8_SA(b, h) + aoff + m * 2048 + k * 1024); } while (0)
; #define PG8_LDB(dst, b, h) do { if constexpr (ABL & 4) break; _Pragma("unroll") for (int n = 0; n < 2; ++n) _Pragma("unroll") for (int k = 0; k < 2; ++k) dst[n][k] = *(const LAS f16x8*)(lds + PG8_SB(b, h) + boff + n * 2048 + k * 1024); } while (0)
; #define PG8_MMA(ai, bj, At, Bt) do { if constexpr (ABL & 2) break; __builtin_amdgcn_s_setprio(1); _Pragma("unroll") for (int m = 0; m < 4; ++m) _Pragma("unroll") for (int n = 0; n < 2; ++n) _Pragma("unroll") for (int k = 0; k < 2; ++k) \
;         acc[ai][bj][m][n] = __builtin_amdgcn_mfma_f32_16x16x32_f16(Bt[n][k], At[m][k], acc[ai][bj][m][n], 0, 0, 0); __builtin_amdgcn_s_setprio(0); } while (0)
; #define PG8_WAIT_V(n) asm volatile("s_waitcnt vmcnt(" #n ")" ::: "memory")
;     ...
;             PG8_LDB(B0, 0, 0); PG8_LDB(B1, 0, 1); PG8_SCHED; PG8_LDA(At, 0, 0); PG8_STAGE(PG8_SA(1, 1), a1 + hstep, voffA);
;             PG8_WAIT_V(8); PG8_WAIT_L(0); PG8_BAR; PG8_MMAF(0, 0, At, B0); PG8_MMAF(0, 1, At, B1); PG8_BAR; PG8_SCHED;
;             const bool fin = last && !has_next;
;             PG8_LDA(At, 0, 1); if (!fin) { PG8_STAGE(PG8_SB(0, 0), b2, voffB); PG8_STAGE(PG8_SB(0, 1), b2 + hstep, voffB); PG8_STAGE(PG8_SA(0, 0), a2, voffA); }
;             if (!fin) PG8_WAIT_V(8); else PG8_WAIT_V(2); PG8_WAIT_L(0); PG8_BAR; PG8_MMAF(1, 0, At, B0); PG8_MMAF(1, 1, At, B1); PG8_BAR; PG8_SCHED;
;             PG8_LDB(B0, 1, 0); PG8_LDB(B1, 1, 1); PG8_SCHED; PG8_LDA(At, 1, 0); if (!fin) PG8_STAGE(PG8_SA(0, 1), a2 + hstep, voffA);
;             if (!fin) PG8_WAIT_V(8); else PG8_WAIT_V(0); PG8_WAIT_L(0); PG8_BAR; PG8_MMA(0, 0, At, B0); PG8_MMA(0, 1, At, B1); PG8_BAR; PG8_SCHED;
;             PG8_LDA(At, 1, 1); if (!fin) { PG8_STAGE(PG8_SB(1, 0), b3, voffB); PG8_STAGE(PG8_SB(1, 1), b3 + hstep, voffB); PG8_STAGE(PG8_SA(1, 0), a3, voffA); }
;             if (!fin) PG8_WAIT_V(8); PG8_WAIT_L(0); PG8_BAR; PG8_MMA(1, 0, At, B0); PG8_MMA(1, 1, At, B1); PG8_BAR; PG8_SCHED;
.LBB0_749:
	s_waitcnt lgkmcnt(0)
	s_barrier
	v_mfma_f32_16x16x32_f16 v[62:65], v[162:165], v[186:189], v[62:65]
	s_setprio 1
	v_mfma_f32_16x16x32_f16 v[62:65], v[166:169], v[190:193], v[62:65]
	v_mfma_f32_16x16x32_f16 v[58:61], v[146:149], v[186:189], v[58:61]
	v_mfma_f32_16x16x32_f16 v[58:61], v[158:161], v[190:193], v[58:61]
	v_mfma_f32_16x16x32_f16 v[46:49], v[162:165], v[178:181], v[46:49]
	v_mfma_f32_16x16x32_f16 v[46:49], v[166:169], v[182:185], v[46:49]
	v_mfma_f32_16x16x32_f16 v[42:45], v[146:149], v[178:181], v[42:45]
	v_mfma_f32_16x16x32_f16 v[42:45], v[158:161], v[182:185], v[42:45]
	v_mfma_f32_16x16x32_f16 v[30:33], v[162:165], v[170:173], v[30:33]
	v_mfma_f32_16x16x32_f16 v[30:33], v[166:169], v[174:177], v[30:33]
	v_mfma_f32_16x16x32_f16 v[26:29], v[146:149], v[170:173], v[26:29]
	v_mfma_f32_16x16x32_f16 v[26:29], v[158:161], v[174:177], v[26:29]
	v_mfma_f32_16x16x32_f16 v[14:17], v[162:165], v[122:125], v[14:17]
	v_mfma_f32_16x16x32_f16 v[14:17], v[166:169], v[134:137], v[14:17]
	v_mfma_f32_16x16x32_f16 v[10:13], v[146:149], v[122:125], v[10:13]
	v_mfma_f32_16x16x32_f16 v[10:13], v[158:161], v[134:137], v[10:13]
	v_mfma_f32_16x16x32_f16 v[54:57], v[98:101], v[186:189], v[54:57]
	v_mfma_f32_16x16x32_f16 v[54:57], v[110:113], v[190:193], v[54:57]
	v_mfma_f32_16x16x32_f16 v[50:53], v[74:77], v[186:189], v[50:53]
	v_mfma_f32_16x16x32_f16 v[50:53], v[86:89], v[190:193], v[50:53]
	v_mfma_f32_16x16x32_f16 v[38:41], v[98:101], v[178:181], v[38:41]
	v_mfma_f32_16x16x32_f16 v[38:41], v[110:113], v[182:185], v[38:41]
	v_mfma_f32_16x16x32_f16 v[34:37], v[74:77], v[178:181], v[34:37]
	v_mfma_f32_16x16x32_f16 v[34:37], v[86:89], v[182:185], v[34:37]
	v_mfma_f32_16x16x32_f16 v[22:25], v[98:101], v[170:173], v[22:25]
	v_mfma_f32_16x16x32_f16 v[22:25], v[110:113], v[174:177], v[22:25]
	v_mfma_f32_16x16x32_f16 v[18:21], v[74:77], v[170:173], v[18:21]
	v_mfma_f32_16x16x32_f16 v[18:21], v[86:89], v[174:177], v[18:21]
	v_mfma_f32_16x16x32_f16 v[6:9], v[98:101], v[122:125], v[6:9]
	v_mfma_f32_16x16x32_f16 v[6:9], v[110:113], v[134:137], v[6:9]
	v_mfma_f32_16x16x32_f16 v[2:5], v[74:77], v[122:125], v[2:5]
	v_mfma_f32_16x16x32_f16 v[2:5], v[86:89], v[134:137], v[2:5]
	s_barrier
	s_setprio 0
	s_add_i32 s59, s59, 2
	s_add_u32 s30, s30, 0x100
	s_addc_u32 s31, s31, 0
	s_cmp_gt_u32 s59, 13
	s_cbranch_scc1 .LBB0_760
.LBB0_750:
	ds_read_b128 v[146:149], v222
	ds_read_b128 v[158:161], v222 offset:1024
	ds_read_b128 v[162:165], v222 offset:2048
	ds_read_b128 v[166:169], v222 offset:3072
	ds_read_b128 v[74:77], v223
	ds_read_b128 v[86:89], v223 offset:1024
	ds_read_b128 v[98:101], v223 offset:2048
	ds_read_b128 v[110:113], v223 offset:3072
	s_mov_b64 s[6:7], s[56:57]
	s_add_u32 s56, s6, 0x100
	s_addc_u32 s57, s7, 0
	s_cmp_eq_u32 s59, 12
	s_cselect_b64 s[26:27], -1, 0
	s_and_b64 s[8:9], s[26:27], exec
	s_cselect_b32 s25, s47, s57
	s_cselect_b32 s24, s55, s56
	s_cselect_b32 s9, s45, s31
	s_cselect_b32 s8, s58, s30
	ds_read_b128 v[170:173], v224
	ds_read_b128 v[174:177], v224 offset:1024
	ds_read_b128 v[178:181], v224 offset:2048
	ds_read_b128 v[182:185], v224 offset:3072
	ds_read_b128 v[186:189], v224 offset:4096
	ds_read_b128 v[190:193], v224 offset:5120
	ds_read_b128 v[194:197], v224 offset:6144
	ds_read_b128 v[198:201], v224 offset:7168
	s_add_u32 s6, s6, 0x40080
	s_addc_u32 s7, s7, 0
	s_add_u32 m0, s14, 0xc000
	s_nop 0
	global_load_lds_dwordx4 v1, s[6:7]
	s_nop 0
	s_add_u32 m0, s14, 0xe000
	s_nop 0
	global_load_lds_dwordx4 v213, s[6:7]
	s_waitcnt vmcnt(8)
	s_waitcnt lgkmcnt(0)
	s_barrier
	v_mfma_f32_16x16x32_f16 v[122:125], v[146:149], v[170:173], v[154:157]
	s_setprio 1
	v_mfma_f32_16x16x32_f16 v[134:137], v[162:165], v[170:173], v[150:153]
	s_waitcnt lgkmcnt(5)
	v_mfma_f32_16x16x32_f16 v[130:133], v[146:149], v[178:181], v[130:133]
	v_mfma_f32_16x16x32_f16 v[126:129], v[162:165], v[178:181], v[126:129]
	s_waitcnt lgkmcnt(3)
	v_mfma_f32_16x16x32_f16 v[106:109], v[146:149], v[186:189], v[106:109]
	v_mfma_f32_16x16x32_f16 v[102:105], v[162:165], v[186:189], v[102:105]
	s_waitcnt lgkmcnt(1)
	v_mfma_f32_16x16x32_f16 v[82:85], v[146:149], v[194:197], v[82:85]
	v_mfma_f32_16x16x32_f16 v[78:81], v[162:165], v[194:197], v[78:81]
	v_mfma_f32_16x16x32_f16 v[122:125], v[158:161], v[174:177], v[122:125]
	v_mfma_f32_16x16x32_f16 v[134:137], v[166:169], v[174:177], v[134:137]
	v_mfma_f32_16x16x32_f16 v[130:133], v[158:161], v[182:185], v[130:133]
	v_mfma_f32_16x16x32_f16 v[126:129], v[166:169], v[182:185], v[126:129]
	v_mfma_f32_16x16x32_f16 v[106:109], v[158:161], v[190:193], v[106:109]
	v_mfma_f32_16x16x32_f16 v[102:105], v[166:169], v[190:193], v[102:105]
	s_waitcnt lgkmcnt(0)
	v_mfma_f32_16x16x32_f16 v[82:85], v[158:161], v[198:201], v[82:85]
	v_mfma_f32_16x16x32_f16 v[78:81], v[166:169], v[198:201], v[78:81]
	v_mfma_f32_16x16x32_f16 v[142:145], v[74:77], v[170:173], v[142:145]
	v_mfma_f32_16x16x32_f16 v[142:145], v[86:89], v[174:177], v[142:145]
	v_mfma_f32_16x16x32_f16 v[138:141], v[98:101], v[170:173], v[138:141]
	v_mfma_f32_16x16x32_f16 v[138:141], v[110:113], v[174:177], v[138:141]
	v_mfma_f32_16x16x32_f16 v[118:121], v[74:77], v[178:181], v[118:121]
	v_mfma_f32_16x16x32_f16 v[118:121], v[86:89], v[182:185], v[118:121]
	v_mfma_f32_16x16x32_f16 v[114:117], v[98:101], v[178:181], v[114:117]
	v_mfma_f32_16x16x32_f16 v[114:117], v[110:113], v[182:185], v[114:117]
	v_mfma_f32_16x16x32_f16 v[94:97], v[74:77], v[186:189], v[94:97]
	v_mfma_f32_16x16x32_f16 v[94:97], v[86:89], v[190:193], v[94:97]
	v_mfma_f32_16x16x32_f16 v[90:93], v[98:101], v[186:189], v[90:93]
	v_mfma_f32_16x16x32_f16 v[90:93], v[110:113], v[190:193], v[90:93]
	v_mfma_f32_16x16x32_f16 v[70:73], v[74:77], v[194:197], v[70:73]
	v_mfma_f32_16x16x32_f16 v[70:73], v[86:89], v[198:201], v[70:73]
	v_mfma_f32_16x16x32_f16 v[66:69], v[98:101], v[194:197], v[66:69]
	v_mfma_f32_16x16x32_f16 v[66:69], v[110:113], v[198:201], v[66:69]
	s_barrier
	s_setprio 0
	ds_read_b128 v[186:189], v224 offset:16384
	ds_read_b128 v[190:193], v224 offset:17408
	ds_read_b128 v[178:181], v224 offset:18432
	ds_read_b128 v[182:185], v224 offset:19456
	ds_read_b128 v[170:173], v224 offset:20480
	ds_read_b128 v[174:177], v224 offset:21504
	ds_read_b128 v[150:153], v224 offset:22528
	ds_read_b128 v[154:157], v224 offset:23552
	s_and_b64 s[6:7], s[4:5], s[26:27]
	s_mov_b64 s[26:27], -1
	s_and_b64 vcc, exec, s[6:7]
	s_cbranch_vccnz .LBB0_752
	s_add_u32 m0, s14, 0x10000
	s_nop 0
	global_load_lds_dwordx4 v209, s[8:9]
	s_nop 0
	s_add_u32 m0, s14, 0x12000
	s_nop 0
	global_load_lds_dwordx4 v219, s[8:9]
	s_add_u32 s26, s8, 0x40000
	s_addc_u32 s27, s9, 0
	s_add_u32 m0, s14, 0x14000
	s_nop 0
	global_load_lds_dwordx4 v209, s[26:27]
	s_nop 0
	s_add_u32 m0, s14, 0x16000
	s_nop 0
	global_load_lds_dwordx4 v219, s[26:27]
	s_mov_b64 s[26:27], 0
	s_add_u32 m0, s14, 0
	s_nop 0
	global_load_lds_dwordx4 v1, s[24:25]
	s_nop 0
	s_add_u32 m0, s14, 0x2000
	s_nop 0
	global_load_lds_dwordx4 v213, s[24:25]
	s_waitcnt vmcnt(8)

; #define PG8_STAGE(bufoff, gbase, voff) do { if constexpr (ABL & 1) break; glds16s<(bufoff)>((voff)[0], (const void*)(gbase), ldsbw); glds16s<(bufoff) + 8192>((voff)[1], (const void*)(gbase), ldsbw); } while (0)
; #define PG8_LDA(dst, b, h) do { if constexpr (ABL & 4) break; _Pragma("unroll") for (int m = 0; m < 4; ++m) _Pragma("unroll") for (int k = 0; k < 2; ++k) dst[m][k] = *(const LAS f16x8*)(lds + PG8_SA(b, h) + aoff + m * 2048 + k * 1024); } while (0)
; #define PG8_LDB(dst, b, h) do { if constexpr (ABL & 4) break; _Pragma("unroll") for (int n = 0; n < 2; ++n) _Pragma("unroll") for (int k = 0; k < 2; ++k) dst[n][k] = *(const LAS f16x8*)(lds + PG8_SB(b, h) + boff + n * 2048 + k * 1024); } while (0)
; #define PG8_MMA(ai, bj, At, Bt) do { if constexpr (ABL & 2) break; __builtin_amdgcn_s_setprio(1); _Pragma("unroll") for (int m = 0; m < 4; ++m) _Pragma("unroll") for (int n = 0; n < 2; ++n) _Pragma("unroll") for (int k = 0; k < 2; ++k) \
;         acc[ai][bj][m][n] = __builtin_amdgcn_mfma_f32_16x16x32_f16(Bt[n][k], At[m][k], acc[ai][bj][m][n], 0, 0, 0); __builtin_amdgcn_s_setprio(0); } while (0)
; #define PG8_MMAF(ai, bj, At, Bt) do { if (t == 0) PG8_MMA0(ai, bj, At, Bt); else PG8_MMA(ai, bj, At, Bt); } while (0)
; #define PG8_WAIT_V(n) asm volatile("s_waitcnt vmcnt(" #n ")" ::: "memory")
; #define PG8_WAIT_L(n) asm volatile("s_waitcnt lgkmcnt(" #n ")" ::: "memory")
; #define PG8_BAR __builtin_amdgcn_s_barrier()
; #define PG8_SCHED __builtin_amdgcn_sched_barrier(0)
;     ...
;             if (!fin) PG8_WAIT_V(8); else PG8_WAIT_V(2); PG8_WAIT_L(0); PG8_BAR; PG8_MMAF(1, 0, At, B0); PG8_MMAF(1, 1, At, B1); PG8_BAR; PG8_SCHED;
;             PG8_LDB(B0, 1, 0); PG8_LDB(B1, 1, 1); PG8_SCHED; PG8_LDA(At, 1, 0); if (!fin) PG8_STAGE(PG8_SA(0, 1), a2 + hstep, voffA);
;             if (!fin) PG8_WAIT_V(8); else PG8_WAIT_V(0); PG8_WAIT_L(0); PG8_BAR; PG8_MMA(0, 0, At, B0); PG8_MMA(0, 1, At, B1); PG8_BAR; PG8_SCHED;
.LBB0_754:
	s_waitcnt lgkmcnt(0)
	s_xor_b64 s[26:27], s[6:7], -1
	s_barrier
	v_mfma_f32_16x16x32_f16 v[62:65], v[146:149], v[186:189], v[62:65]
	s_setprio 1
	v_mfma_f32_16x16x32_f16 v[62:65], v[158:161], v[190:193], v[62:65]
	v_mfma_f32_16x16x32_f16 v[58:61], v[162:165], v[186:189], v[58:61]
	v_mfma_f32_16x16x32_f16 v[58:61], v[166:169], v[190:193], v[58:61]
	v_mfma_f32_16x16x32_f16 v[46:49], v[146:149], v[178:181], v[46:49]
	v_mfma_f32_16x16x32_f16 v[46:49], v[158:161], v[182:185], v[46:49]
	v_mfma_f32_16x16x32_f16 v[42:45], v[162:165], v[178:181], v[42:45]
	v_mfma_f32_16x16x32_f16 v[42:45], v[166:169], v[182:185], v[42:45]
	v_mfma_f32_16x16x32_f16 v[30:33], v[146:149], v[170:173], v[30:33]
	v_mfma_f32_16x16x32_f16 v[30:33], v[158:161], v[174:177], v[30:33]
	v_mfma_f32_16x16x32_f16 v[26:29], v[162:165], v[170:173], v[26:29]
	v_mfma_f32_16x16x32_f16 v[26:29], v[166:169], v[174:177], v[26:29]
	v_mfma_f32_16x16x32_f16 v[14:17], v[146:149], v[150:153], v[14:17]
	v_mfma_f32_16x16x32_f16 v[14:17], v[158:161], v[154:157], v[14:17]
	v_mfma_f32_16x16x32_f16 v[10:13], v[162:165], v[150:153], v[10:13]
	v_mfma_f32_16x16x32_f16 v[10:13], v[166:169], v[154:157], v[10:13]
	v_mfma_f32_16x16x32_f16 v[54:57], v[74:77], v[186:189], v[54:57]
	v_mfma_f32_16x16x32_f16 v[54:57], v[86:89], v[190:193], v[54:57]
	v_mfma_f32_16x16x32_f16 v[50:53], v[98:101], v[186:189], v[50:53]
	v_mfma_f32_16x16x32_f16 v[50:53], v[110:113], v[190:193], v[50:53]
	v_mfma_f32_16x16x32_f16 v[38:41], v[74:77], v[178:181], v[38:41]
	v_mfma_f32_16x16x32_f16 v[38:41], v[86:89], v[182:185], v[38:41]
	v_mfma_f32_16x16x32_f16 v[34:37], v[98:101], v[178:181], v[34:37]
	v_mfma_f32_16x16x32_f16 v[34:37], v[110:113], v[182:185], v[34:37]
	v_mfma_f32_16x16x32_f16 v[22:25], v[74:77], v[170:173], v[22:25]
	v_mfma_f32_16x16x32_f16 v[22:25], v[86:89], v[174:177], v[22:25]
	v_mfma_f32_16x16x32_f16 v[18:21], v[98:101], v[170:173], v[18:21]
	v_mfma_f32_16x16x32_f16 v[18:21], v[110:113], v[174:177], v[18:21]
	v_mfma_f32_16x16x32_f16 v[6:9], v[74:77], v[150:153], v[6:9]
	v_mfma_f32_16x16x32_f16 v[6:9], v[86:89], v[154:157], v[6:9]
	v_mfma_f32_16x16x32_f16 v[2:5], v[98:101], v[150:153], v[2:5]
	v_mfma_f32_16x16x32_f16 v[2:5], v[110:113], v[154:157], v[2:5]
	s_barrier
	s_setprio 0
	ds_read_b128 v[162:165], v225
	ds_read_b128 v[166:169], v225 offset:1024
	ds_read_b128 v[146:149], v225 offset:2048
	ds_read_b128 v[158:161], v225 offset:3072
	ds_read_b128 v[98:101], v226
	ds_read_b128 v[110:113], v226 offset:1024
	ds_read_b128 v[74:77], v226 offset:2048
	ds_read_b128 v[86:89], v226 offset:3072
	ds_read_b128 v[194:197], v224 offset:32768
	ds_read_b128 v[198:201], v224 offset:33792
	ds_read_b128 v[186:189], v224 offset:34816
	ds_read_b128 v[190:193], v224 offset:35840
	ds_read_b128 v[178:181], v224 offset:36864
	ds_read_b128 v[182:185], v224 offset:37888
	ds_read_b128 v[170:173], v224 offset:38912
	ds_read_b128 v[174:177], v224 offset:39936
	v_cndmask_b32_e64 v150, 0, 1, s[26:27]
	v_cmp_ne_u32_e64 s[6:7], 1, v150
	s_andn2_b64 vcc, exec, s[26:27]
	s_mov_b64 s[26:27], -1
	s_cbranch_vccnz .LBB0_756
	s_add_u32 s26, s24, 0x40000
	s_addc_u32 s27, s25, 0
	s_add_u32 m0, s14, 0x4000
	s_nop 0
	global_load_lds_dwordx4 v1, s[26:27]
	s_nop 0
	s_add_u32 m0, s14, 0x6000
	s_nop 0
	global_load_lds_dwordx4 v213, s[26:27]
	s_waitcnt vmcnt(8)
	s_mov_b64 s[26:27], 0

; #define PG8_STAGE(bufoff, gbase, voff) do { if constexpr (ABL & 1) break; glds16s<(bufoff)>((voff)[0], (const void*)(gbase), ldsbw); glds16s<(bufoff) + 8192>((voff)[1], (const void*)(gbase), ldsbw); } while (0)
; #define PG8_LDA(dst, b, h) do { if constexpr (ABL & 4) break; _Pragma("unroll") for (int m = 0; m < 4; ++m) _Pragma("unroll") for (int k = 0; k < 2; ++k) dst[m][k] = *(const LAS f16x8*)(lds + PG8_SA(b, h) + aoff + m * 2048 + k * 1024); } while (0)
; #define PG8_LDB(dst, b, h) do { if constexpr (ABL & 4) break; _Pragma("unroll") for (int n = 0; n < 2; ++n) _Pragma("unroll") for (int k = 0; k < 2; ++k) dst[n][k] = *(const LAS f16x8*)(lds + PG8_SB(b, h) + boff + n * 2048 + k * 1024); } while (0)
; #define PG8_BAR __builtin_amdgcn_s_barrier()
;     ...
;         for (int t = 0; t < nt; t += 2) {
;             const bool last = (t == nt - 2);
;             const char* a1 = cA + (size_t)(t + 1) * kstep;
;             const char* a2 = last ? nA : cA + (size_t)(t + 2) * kstep; const char* b2 = last ? nB : cB + (size_t)(t + 2) * kstep;
;             const char* a3 = a2 + kstep; const char* b3 = b2 + kstep;
;             if (last && has_next) S.a_ready(nxt);
;             if constexpr (SP2) {
;             PG8_LDB(B0, 0, 0); PG8_LDB(B1, 0, 1); PG8_SCHED; PG8_LDA(At, 0, 0); PG8_STAGE(PG8_SA(1, 1), a1 + hstep, voffA);
;             PG8_WAIT_V(8); PG8_WAIT_L(0); PG8_BAR; PG8_MMAF(0, 0, At, B0); PG8_MMAF(0, 1, At, B1); PG8_BAR; PG8_SCHED;
;             const bool fin = last && !has_next;
;             PG8_LDA(At, 0, 1); if (!fin) { PG8_STAGE(PG8_SB(0, 0), b2, voffB); PG8_STAGE(PG8_SB(0, 1), b2 + hstep, voffB); PG8_STAGE(PG8_SA(0, 0), a2, voffA); }
;             if (!fin) PG8_WAIT_V(8); else PG8_WAIT_V(2); PG8_WAIT_L(0); PG8_BAR; PG8_MMAF(1, 0, At, B0); PG8_MMAF(1, 1, At, B1); PG8_BAR; PG8_SCHED;
;             PG8_LDB(B0, 1, 0); PG8_LDB(B1, 1, 1); PG8_SCHED; PG8_LDA(At, 1, 0); if (!fin) PG8_STAGE(PG8_SA(0, 1), a2 + hstep, voffA);
;             if (!fin) PG8_WAIT_V(8); else PG8_WAIT_V(0); PG8_WAIT_L(0); PG8_BAR; PG8_MMA(0, 0, At, B0); PG8_MMA(0, 1, At, B1); PG8_BAR; PG8_SCHED;
;             PG8_LDA(At, 1, 1); if (!fin) { PG8_STAGE(PG8_SB(1, 0), b3, voffB); PG8_STAGE(PG8_SB(1, 1), b3 + hstep, voffB); PG8_STAGE(PG8_SA(1, 0), a3, voffA); }
;             if (!fin) PG8_WAIT_V(8); PG8_WAIT_L(0); PG8_BAR; PG8_MMA(1, 0, At, B0); PG8_MMA(1, 1, At, B1); PG8_BAR; PG8_SCHED;
.LBB0_842:
	s_waitcnt lgkmcnt(0)
	s_barrier
	v_mfma_f32_16x16x32_f16 v[58:61], v[146:149], v[186:189], v[58:61]
	s_setprio 1
	v_mfma_f32_16x16x32_f16 v[58:61], v[150:153], v[190:193], v[58:61]
	v_mfma_f32_16x16x32_f16 v[50:53], v[154:157], v[186:189], v[50:53]
	v_mfma_f32_16x16x32_f16 v[50:53], v[158:161], v[190:193], v[50:53]
	v_mfma_f32_16x16x32_f16 v[42:45], v[146:149], v[178:181], v[42:45]
	v_mfma_f32_16x16x32_f16 v[42:45], v[150:153], v[182:185], v[42:45]
	v_mfma_f32_16x16x32_f16 v[34:37], v[154:157], v[178:181], v[34:37]
	v_mfma_f32_16x16x32_f16 v[34:37], v[158:161], v[182:185], v[34:37]
	v_mfma_f32_16x16x32_f16 v[26:29], v[146:149], v[170:173], v[26:29]
	v_mfma_f32_16x16x32_f16 v[26:29], v[150:153], v[174:177], v[26:29]
	v_mfma_f32_16x16x32_f16 v[18:21], v[154:157], v[170:173], v[18:21]
	v_mfma_f32_16x16x32_f16 v[18:21], v[158:161], v[174:177], v[18:21]
	v_mfma_f32_16x16x32_f16 v[10:13], v[146:149], v[162:165], v[10:13]
	v_mfma_f32_16x16x32_f16 v[10:13], v[150:153], v[166:169], v[10:13]
	v_mfma_f32_16x16x32_f16 v[2:5], v[154:157], v[162:165], v[2:5]
	v_mfma_f32_16x16x32_f16 v[2:5], v[158:161], v[166:169], v[2:5]
	v_mfma_f32_16x16x32_f16 v[66:69], v[130:133], v[186:189], v[66:69]
	v_mfma_f32_16x16x32_f16 v[66:69], v[134:137], v[190:193], v[66:69]
	v_mfma_f32_16x16x32_f16 v[54:57], v[138:141], v[186:189], v[54:57]
	v_mfma_f32_16x16x32_f16 v[54:57], v[142:145], v[190:193], v[54:57]
	v_mfma_f32_16x16x32_f16 v[46:49], v[130:133], v[178:181], v[46:49]
	v_mfma_f32_16x16x32_f16 v[46:49], v[134:137], v[182:185], v[46:49]
	v_mfma_f32_16x16x32_f16 v[38:41], v[138:141], v[178:181], v[38:41]
	v_mfma_f32_16x16x32_f16 v[38:41], v[142:145], v[182:185], v[38:41]
	v_mfma_f32_16x16x32_f16 v[30:33], v[130:133], v[170:173], v[30:33]
	v_mfma_f32_16x16x32_f16 v[30:33], v[134:137], v[174:177], v[30:33]
	v_mfma_f32_16x16x32_f16 v[22:25], v[138:141], v[170:173], v[22:25]
	v_mfma_f32_16x16x32_f16 v[22:25], v[142:145], v[174:177], v[22:25]
	v_mfma_f32_16x16x32_f16 v[14:17], v[130:133], v[162:165], v[14:17]
	v_mfma_f32_16x16x32_f16 v[14:17], v[134:137], v[166:169], v[14:17]
	v_mfma_f32_16x16x32_f16 v[6:9], v[138:141], v[162:165], v[6:9]
	v_mfma_f32_16x16x32_f16 v[6:9], v[142:145], v[166:169], v[6:9]
	s_barrier
	s_setprio 0
	s_add_i32 s55, s55, 2
	s_add_u32 s53, s53, 0x100
	s_addc_u32 s54, s54, 0
	s_cmp_gt_u32 s55, 13
	s_cbranch_scc1 .LBB0_853
.LBB0_843:
	ds_read_b128 v[146:149], v210
	ds_read_b128 v[150:153], v210 offset:1024
	ds_read_b128 v[154:157], v210 offset:2048
	ds_read_b128 v[158:161], v210 offset:3072
	ds_read_b128 v[130:133], v211
	ds_read_b128 v[134:137], v211 offset:1024
	ds_read_b128 v[138:141], v211 offset:2048
	ds_read_b128 v[142:145], v211 offset:3072
	s_mov_b64 s[6:7], s[48:49]
	s_add_u32 s48, s6, 0x100
	s_addc_u32 s49, s7, 0
	s_cmp_eq_u32 s55, 12
	s_cselect_b64 s[26:27], -1, 0
	s_and_b64 s[8:9], s[26:27], exec
	s_cselect_b32 s25, s41, s49
	s_cselect_b32 s24, s51, s48
	s_cselect_b32 s9, s39, s54
	s_cselect_b32 s8, s52, s53
	ds_read_b128 v[162:165], v212
	ds_read_b128 v[166:169], v212 offset:1024
	ds_read_b128 v[170:173], v212 offset:2048
	ds_read_b128 v[174:177], v212 offset:3072
	ds_read_b128 v[178:181], v212 offset:4096
	ds_read_b128 v[182:185], v212 offset:5120
	ds_read_b128 v[186:189], v212 offset:6144
	ds_read_b128 v[190:193], v212 offset:7168
	s_add_u32 s6, s6, 0x40080
	s_addc_u32 s7, s7, 0
	s_add_u32 m0, s14, 0xc000
	s_nop 0
	global_load_lds_dwordx4 v206, s[6:7]
	s_nop 0
	s_add_u32 m0, s14, 0xe000
	s_nop 0
	global_load_lds_dwordx4 v208, s[6:7]
	s_waitcnt vmcnt(8)
	s_waitcnt lgkmcnt(0)
	s_barrier
	v_mfma_f32_16x16x32_f16 v[114:117], v[146:149], v[162:165], v[114:117]
	s_setprio 1
	v_mfma_f32_16x16x32_f16 v[114:117], v[150:153], v[166:169], v[114:117]
	v_mfma_f32_16x16x32_f16 v[110:113], v[154:157], v[162:165], v[110:113]
	v_mfma_f32_16x16x32_f16 v[110:113], v[158:161], v[166:169], v[110:113]
	v_mfma_f32_16x16x32_f16 v[106:109], v[146:149], v[170:173], v[106:109]
	v_mfma_f32_16x16x32_f16 v[106:109], v[150:153], v[174:177], v[106:109]
	v_mfma_f32_16x16x32_f16 v[98:101], v[154:157], v[170:173], v[98:101]
	v_mfma_f32_16x16x32_f16 v[98:101], v[158:161], v[174:177], v[98:101]
	v_mfma_f32_16x16x32_f16 v[90:93], v[146:149], v[178:181], v[90:93]
	v_mfma_f32_16x16x32_f16 v[90:93], v[150:153], v[182:185], v[90:93]
	v_mfma_f32_16x16x32_f16 v[82:85], v[154:157], v[178:181], v[82:85]
	v_mfma_f32_16x16x32_f16 v[82:85], v[158:161], v[182:185], v[82:85]
	v_mfma_f32_16x16x32_f16 v[74:77], v[146:149], v[186:189], v[74:77]
	v_mfma_f32_16x16x32_f16 v[74:77], v[150:153], v[190:193], v[74:77]
	v_mfma_f32_16x16x32_f16 v[62:65], v[154:157], v[186:189], v[62:65]
	v_mfma_f32_16x16x32_f16 v[62:65], v[158:161], v[190:193], v[62:65]
	v_mfma_f32_16x16x32_f16 v[126:129], v[130:133], v[162:165], v[126:129]
	v_mfma_f32_16x16x32_f16 v[126:129], v[134:137], v[166:169], v[126:129]
	v_mfma_f32_16x16x32_f16 v[122:125], v[138:141], v[162:165], v[122:125]
	v_mfma_f32_16x16x32_f16 v[122:125], v[142:145], v[166:169], v[122:125]
	v_mfma_f32_16x16x32_f16 v[118:121], v[130:133], v[170:173], v[118:121]
	v_mfma_f32_16x16x32_f16 v[118:121], v[134:137], v[174:177], v[118:121]
	v_mfma_f32_16x16x32_f16 v[102:105], v[138:141], v[170:173], v[102:105]
	v_mfma_f32_16x16x32_f16 v[102:105], v[142:145], v[174:177], v[102:105]
	v_mfma_f32_16x16x32_f16 v[94:97], v[130:133], v[178:181], v[94:97]
	v_mfma_f32_16x16x32_f16 v[94:97], v[134:137], v[182:185], v[94:97]
	v_mfma_f32_16x16x32_f16 v[86:89], v[138:141], v[178:181], v[86:89]
	v_mfma_f32_16x16x32_f16 v[86:89], v[142:145], v[182:185], v[86:89]
	v_mfma_f32_16x16x32_f16 v[78:81], v[130:133], v[186:189], v[78:81]
	v_mfma_f32_16x16x32_f16 v[78:81], v[134:137], v[190:193], v[78:81]
	v_mfma_f32_16x16x32_f16 v[70:73], v[138:141], v[186:189], v[70:73]
	v_mfma_f32_16x16x32_f16 v[70:73], v[142:145], v[190:193], v[70:73]
	s_barrier
	s_setprio 0
	ds_read_b128 v[186:189], v212 offset:16384
	ds_read_b128 v[190:193], v212 offset:17408
	ds_read_b128 v[178:181], v212 offset:18432
	ds_read_b128 v[182:185], v212 offset:19456
	ds_read_b128 v[170:173], v212 offset:20480
	ds_read_b128 v[174:177], v212 offset:21504
	ds_read_b128 v[162:165], v212 offset:22528
	ds_read_b128 v[166:169], v212 offset:23552
	s_and_b64 s[6:7], s[4:5], s[26:27]
	s_mov_b64 s[26:27], -1
	s_and_b64 vcc, exec, s[6:7]
	s_cbranch_vccnz .LBB0_845
	s_add_u32 m0, s14, 0x10000
	s_nop 0
	global_load_lds_dwordx4 v207, s[8:9]
	s_nop 0
	s_add_u32 m0, s14, 0x12000
	s_nop 0
	global_load_lds_dwordx4 v209, s[8:9]
	s_add_u32 s26, s8, 0x40000
	s_addc_u32 s27, s9, 0
	s_add_u32 m0, s14, 0x14000
	s_nop 0
	global_load_lds_dwordx4 v207, s[26:27]
	s_nop 0
	s_add_u32 m0, s14, 0x16000
	s_nop 0
	global_load_lds_dwordx4 v209, s[26:27]
	s_mov_b64 s[26:27], 0
	s_add_u32 m0, s14, 0
	s_nop 0
	global_load_lds_dwordx4 v206, s[24:25]
	s_nop 0
	s_add_u32 m0, s14, 0x2000
	s_nop 0
	global_load_lds_dwordx4 v208, s[24:25]
	s_waitcnt vmcnt(8)

; #define PG8_STAGE(bufoff, gbase, voff) do { if constexpr (ABL & 1) break; glds16s<(bufoff)>((voff)[0], (const void*)(gbase), ldsbw); glds16s<(bufoff) + 8192>((voff)[1], (const void*)(gbase), ldsbw); } while (0)
; #define PG8_LDA(dst, b, h) do { if constexpr (ABL & 4) break; _Pragma("unroll") for (int m = 0; m < 4; ++m) _Pragma("unroll") for (int k = 0; k < 2; ++k) dst[m][k] = *(const LAS f16x8*)(lds + PG8_SA(b, h) + aoff + m * 2048 + k * 1024); } while (0)
; #define PG8_LDB(dst, b, h) do { if constexpr (ABL & 4) break; _Pragma("unroll") for (int n = 0; n < 2; ++n) _Pragma("unroll") for (int k = 0; k < 2; ++k) dst[n][k] = *(const LAS f16x8*)(lds + PG8_SB(b, h) + boff + n * 2048 + k * 1024); } while (0)
; #define PG8_MMA(ai, bj, At, Bt) do { if constexpr (ABL & 2) break; __builtin_amdgcn_s_setprio(1); _Pragma("unroll") for (int m = 0; m < 4; ++m) _Pragma("unroll") for (int n = 0; n < 2; ++n) _Pragma("unroll") for (int k = 0; k < 2; ++k) \
;         acc[ai][bj][m][n] = __builtin_amdgcn_mfma_f32_16x16x32_f16(Bt[n][k], At[m][k], acc[ai][bj][m][n], 0, 0, 0); __builtin_amdgcn_s_setprio(0); } while (0)
; #define PG8_MMAF(ai, bj, At, Bt) do { if (t == 0) PG8_MMA0(ai, bj, At, Bt); else PG8_MMA(ai, bj, At, Bt); } while (0)
; #define PG8_WAIT_V(n) asm volatile("s_waitcnt vmcnt(" #n ")" ::: "memory")
; #define PG8_WAIT_L(n) asm volatile("s_waitcnt lgkmcnt(" #n ")" ::: "memory")
; #define PG8_BAR __builtin_amdgcn_s_barrier()
; #define PG8_SCHED __builtin_amdgcn_sched_barrier(0)
;     ...
;             if (!fin) PG8_WAIT_V(8); else PG8_WAIT_V(2); PG8_WAIT_L(0); PG8_BAR; PG8_MMAF(1, 0, At, B0); PG8_MMAF(1, 1, At, B1); PG8_BAR; PG8_SCHED;
;             PG8_LDB(B0, 1, 0); PG8_LDB(B1, 1, 1); PG8_SCHED; PG8_LDA(At, 1, 0); if (!fin) PG8_STAGE(PG8_SA(0, 1), a2 + hstep, voffA);
;             if (!fin) PG8_WAIT_V(8); else PG8_WAIT_V(0); PG8_WAIT_L(0); PG8_BAR; PG8_MMA(0, 0, At, B0); PG8_MMA(0, 1, At, B1); PG8_BAR; PG8_SCHED;
.LBB0_847:
	s_waitcnt lgkmcnt(0)
	s_xor_b64 s[26:27], s[6:7], -1
	s_barrier
	v_mfma_f32_16x16x32_f16 v[58:61], v[146:149], v[186:189], v[58:61]
	s_setprio 1
	v_mfma_f32_16x16x32_f16 v[58:61], v[150:153], v[190:193], v[58:61]
	v_mfma_f32_16x16x32_f16 v[50:53], v[154:157], v[186:189], v[50:53]
	v_mfma_f32_16x16x32_f16 v[50:53], v[158:161], v[190:193], v[50:53]
	v_mfma_f32_16x16x32_f16 v[42:45], v[146:149], v[178:181], v[42:45]
	v_mfma_f32_16x16x32_f16 v[42:45], v[150:153], v[182:185], v[42:45]
	v_mfma_f32_16x16x32_f16 v[34:37], v[154:157], v[178:181], v[34:37]
	v_mfma_f32_16x16x32_f16 v[34:37], v[158:161], v[182:185], v[34:37]
	v_mfma_f32_16x16x32_f16 v[26:29], v[146:149], v[170:173], v[26:29]
	v_mfma_f32_16x16x32_f16 v[26:29], v[150:153], v[174:177], v[26:29]
	v_mfma_f32_16x16x32_f16 v[18:21], v[154:157], v[170:173], v[18:21]
	v_mfma_f32_16x16x32_f16 v[18:21], v[158:161], v[174:177], v[18:21]
	v_mfma_f32_16x16x32_f16 v[10:13], v[146:149], v[162:165], v[10:13]
	v_mfma_f32_16x16x32_f16 v[10:13], v[150:153], v[166:169], v[10:13]
	v_mfma_f32_16x16x32_f16 v[2:5], v[154:157], v[162:165], v[2:5]
	v_mfma_f32_16x16x32_f16 v[2:5], v[158:161], v[166:169], v[2:5]
	v_mfma_f32_16x16x32_f16 v[66:69], v[130:133], v[186:189], v[66:69]
	v_mfma_f32_16x16x32_f16 v[66:69], v[134:137], v[190:193], v[66:69]
	v_mfma_f32_16x16x32_f16 v[54:57], v[138:141], v[186:189], v[54:57]
	v_mfma_f32_16x16x32_f16 v[54:57], v[142:145], v[190:193], v[54:57]
	v_mfma_f32_16x16x32_f16 v[46:49], v[130:133], v[178:181], v[46:49]
	v_mfma_f32_16x16x32_f16 v[46:49], v[134:137], v[182:185], v[46:49]
	v_mfma_f32_16x16x32_f16 v[38:41], v[138:141], v[178:181], v[38:41]
	v_mfma_f32_16x16x32_f16 v[38:41], v[142:145], v[182:185], v[38:41]
	v_mfma_f32_16x16x32_f16 v[30:33], v[130:133], v[170:173], v[30:33]
	v_mfma_f32_16x16x32_f16 v[30:33], v[134:137], v[174:177], v[30:33]
	v_mfma_f32_16x16x32_f16 v[22:25], v[138:141], v[170:173], v[22:25]
	v_mfma_f32_16x16x32_f16 v[22:25], v[142:145], v[174:177], v[22:25]
	v_mfma_f32_16x16x32_f16 v[14:17], v[130:133], v[162:165], v[14:17]
	v_mfma_f32_16x16x32_f16 v[14:17], v[134:137], v[166:169], v[14:17]
	v_mfma_f32_16x16x32_f16 v[6:9], v[138:141], v[162:165], v[6:9]
	v_mfma_f32_16x16x32_f16 v[6:9], v[142:145], v[166:169], v[6:9]
	s_barrier
	s_setprio 0
	ds_read_b128 v[146:149], v213
	ds_read_b128 v[150:153], v213 offset:1024
	ds_read_b128 v[154:157], v213 offset:2048
	ds_read_b128 v[158:161], v213 offset:3072
	ds_read_b128 v[130:133], v214
	ds_read_b128 v[134:137], v214 offset:1024
	ds_read_b128 v[138:141], v214 offset:2048
	ds_read_b128 v[142:145], v214 offset:3072
	ds_read_b128 v[186:189], v212 offset:32768
	ds_read_b128 v[190:193], v212 offset:33792
	ds_read_b128 v[178:181], v212 offset:34816
	ds_read_b128 v[182:185], v212 offset:35840
	ds_read_b128 v[170:173], v212 offset:36864
	ds_read_b128 v[174:177], v212 offset:37888
	ds_read_b128 v[162:165], v212 offset:38912
	ds_read_b128 v[166:169], v212 offset:39936
	v_cndmask_b32_e64 v216, 0, 1, s[26:27]
	v_cmp_ne_u32_e64 s[6:7], 1, v216
	s_andn2_b64 vcc, exec, s[26:27]
	s_mov_b64 s[26:27], -1
	s_cbranch_vccnz .LBB0_849
	s_add_u32 s26, s24, 0x40000
	s_addc_u32 s27, s25, 0
	s_add_u32 m0, s14, 0x4000
	s_nop 0
	global_load_lds_dwordx4 v206, s[26:27]
	s_nop 0
	s_add_u32 m0, s14, 0x6000
	s_nop 0
	global_load_lds_dwordx4 v208, s[26:27]
	s_waitcnt vmcnt(8)
	s_mov_b64 s[26:27], 0

; #define PG8_STAGE(bufoff, gbase, voff) do { if constexpr (ABL & 1) break; glds16s<(bufoff)>((voff)[0], (const void*)(gbase), ldsbw); glds16s<(bufoff) + 8192>((voff)[1], (const void*)(gbase), ldsbw); } while (0)
; #define PG8_LDA(dst, b, h) do { if constexpr (ABL & 4) break; _Pragma("unroll") for (int m = 0; m < 4; ++m) _Pragma("unroll") for (int k = 0; k < 2; ++k) dst[m][k] = *(const LAS f16x8*)(lds + PG8_SA(b, h) + aoff + m * 2048 + k * 1024); } while (0)
; #define PG8_MMA(ai, bj, At, Bt) do { if constexpr (ABL & 2) break; __builtin_amdgcn_s_setprio(1); _Pragma("unroll") for (int m = 0; m < 4; ++m) _Pragma("unroll") for (int n = 0; n < 2; ++n) _Pragma("unroll") for (int k = 0; k < 2; ++k) \
;         acc[ai][bj][m][n] = __builtin_amdgcn_mfma_f32_16x16x32_f16(Bt[n][k], At[m][k], acc[ai][bj][m][n], 0, 0, 0); __builtin_amdgcn_s_setprio(0); } while (0)
; #define PG8_WAIT_V(n) asm volatile("s_waitcnt vmcnt(" #n ")" ::: "memory")
; #define PG8_WAIT_L(n) asm volatile("s_waitcnt lgkmcnt(" #n ")" ::: "memory")
; #define PG8_BAR __builtin_amdgcn_s_barrier()
; #define PG8_SCHED __builtin_amdgcn_sched_barrier(0)
;     ...
;             if (!fin) PG8_WAIT_V(8); else PG8_WAIT_V(0); PG8_WAIT_L(0); PG8_BAR; PG8_MMA(0, 0, At, B0); PG8_MMA(0, 1, At, B1); PG8_BAR; PG8_SCHED;
;             PG8_LDA(At, 1, 1); if (!fin) { PG8_STAGE(PG8_SB(1, 0), b3, voffB); PG8_STAGE(PG8_SB(1, 1), b3 + hstep, voffB); PG8_STAGE(PG8_SA(1, 0), a3, voffA); }
;             if (!fin) PG8_WAIT_V(8); PG8_WAIT_L(0); PG8_BAR; PG8_MMA(1, 0, At, B0); PG8_MMA(1, 1, At, B1); PG8_BAR; PG8_SCHED;
.LBB0_851:
	s_waitcnt lgkmcnt(0)
	s_barrier
	v_mfma_f32_16x16x32_f16 v[114:117], v[146:149], v[186:189], v[114:117]
	s_setprio 1
	v_mfma_f32_16x16x32_f16 v[114:117], v[150:153], v[190:193], v[114:117]
	v_mfma_f32_16x16x32_f16 v[110:113], v[154:157], v[186:189], v[110:113]
	v_mfma_f32_16x16x32_f16 v[110:113], v[158:161], v[190:193], v[110:113]
	v_mfma_f32_16x16x32_f16 v[106:109], v[146:149], v[178:181], v[106:109]
	v_mfma_f32_16x16x32_f16 v[106:109], v[150:153], v[182:185], v[106:109]
	v_mfma_f32_16x16x32_f16 v[98:101], v[154:157], v[178:181], v[98:101]
	v_mfma_f32_16x16x32_f16 v[98:101], v[158:161], v[182:185], v[98:101]
	v_mfma_f32_16x16x32_f16 v[90:93], v[146:149], v[170:173], v[90:93]
	v_mfma_f32_16x16x32_f16 v[90:93], v[150:153], v[174:177], v[90:93]
	v_mfma_f32_16x16x32_f16 v[82:85], v[154:157], v[170:173], v[82:85]
	v_mfma_f32_16x16x32_f16 v[82:85], v[158:161], v[174:177], v[82:85]
	v_mfma_f32_16x16x32_f16 v[74:77], v[146:149], v[162:165], v[74:77]
	v_mfma_f32_16x16x32_f16 v[74:77], v[150:153], v[166:169], v[74:77]
	v_mfma_f32_16x16x32_f16 v[62:65], v[154:157], v[162:165], v[62:65]
	v_mfma_f32_16x16x32_f16 v[62:65], v[158:161], v[166:169], v[62:65]
	v_mfma_f32_16x16x32_f16 v[126:129], v[130:133], v[186:189], v[126:129]
	v_mfma_f32_16x16x32_f16 v[126:129], v[134:137], v[190:193], v[126:129]
	v_mfma_f32_16x16x32_f16 v[122:125], v[138:141], v[186:189], v[122:125]
	v_mfma_f32_16x16x32_f16 v[122:125], v[142:145], v[190:193], v[122:125]
	v_mfma_f32_16x16x32_f16 v[118:121], v[130:133], v[178:181], v[118:121]
	v_mfma_f32_16x16x32_f16 v[118:121], v[134:137], v[182:185], v[118:121]
	v_mfma_f32_16x16x32_f16 v[102:105], v[138:141], v[178:181], v[102:105]
	v_mfma_f32_16x16x32_f16 v[102:105], v[142:145], v[182:185], v[102:105]
	v_mfma_f32_16x16x32_f16 v[94:97], v[130:133], v[170:173], v[94:97]
	v_mfma_f32_16x16x32_f16 v[94:97], v[134:137], v[174:177], v[94:97]
	v_mfma_f32_16x16x32_f16 v[86:89], v[138:141], v[170:173], v[86:89]
	v_mfma_f32_16x16x32_f16 v[86:89], v[142:145], v[174:177], v[86:89]
	v_mfma_f32_16x16x32_f16 v[78:81], v[130:133], v[162:165], v[78:81]
	v_mfma_f32_16x16x32_f16 v[78:81], v[134:137], v[166:169], v[78:81]
	v_mfma_f32_16x16x32_f16 v[70:73], v[138:141], v[162:165], v[70:73]
	v_mfma_f32_16x16x32_f16 v[70:73], v[142:145], v[166:169], v[70:73]
	s_barrier
	s_setprio 0
	ds_read_b128 v[186:189], v212 offset:49152
	ds_read_b128 v[190:193], v212 offset:50176
	ds_read_b128 v[178:181], v212 offset:51200
	ds_read_b128 v[182:185], v212 offset:52224
	ds_read_b128 v[170:173], v212 offset:53248
	ds_read_b128 v[174:177], v212 offset:54272
	ds_read_b128 v[162:165], v212 offset:55296
	ds_read_b128 v[166:169], v212 offset:56320
	s_and_b64 vcc, exec, s[6:7]
	s_cbranch_vccnz .LBB0_842
	s_add_u32 s6, s24, 0x80
	s_addc_u32 s7, s25, 0
	s_add_u32 s24, s8, 0x80
	s_addc_u32 s25, s9, 0
	s_add_u32 m0, s14, 0x18000
	s_nop 0
	global_load_lds_dwordx4 v207, s[24:25]
	s_nop 0
	s_add_u32 m0, s14, 0x1a000
	s_nop 0
	global_load_lds_dwordx4 v209, s[24:25]
	s_add_u32 s8, s8, 0x40080
	s_addc_u32 s9, s9, 0
	s_add_u32 m0, s14, 0x1c000
	s_nop 0
	global_load_lds_dwordx4 v207, s[8:9]
	s_nop 0
	s_add_u32 m0, s14, 0x1e000
	s_nop 0
	global_load_lds_dwordx4 v209, s[8:9]
	s_nop 0
	s_add_u32 m0, s14, 0x8000
	s_nop 0
	global_load_lds_dwordx4 v206, s[6:7]
	s_nop 0
	s_add_u32 m0, s14, 0xa000
	s_nop 0
	global_load_lds_dwordx4 v208, s[6:7]
	s_waitcnt vmcnt(8)
	s_branch .LBB0_842

; #define PG8_STAGE(bufoff, gbase, voff) do { if constexpr (ABL & 1) break; glds16s<(bufoff)>((voff)[0], (const void*)(gbase), ldsbw); glds16s<(bufoff) + 8192>((voff)[1], (const void*)(gbase), ldsbw); } while (0)
; #define PG8_LDA(dst, b, h) do { if constexpr (ABL & 4) break; _Pragma("unroll") for (int m = 0; m < 4; ++m) _Pragma("unroll") for (int k = 0; k < 2; ++k) dst[m][k] = *(const LAS f16x8*)(lds + PG8_SA(b, h) + aoff + m * 2048 + k * 1024); } while (0)
; #define PG8_LDB(dst, b, h) do { if constexpr (ABL & 4) break; _Pragma("unroll") for (int n = 0; n < 2; ++n) _Pragma("unroll") for (int k = 0; k < 2; ++k) dst[n][k] = *(const LAS f16x8*)(lds + PG8_SB(b, h) + boff + n * 2048 + k * 1024); } while (0)
; #define PG8_BAR __builtin_amdgcn_s_barrier()
;     ...
;         for (int t = 0; t < nt; t += 2) {
;             const bool last = (t == nt - 2);
;             const char* a1 = cA + (size_t)(t + 1) * kstep;
;             const char* a2 = last ? nA : cA + (size_t)(t + 2) * kstep; const char* b2 = last ? nB : cB + (size_t)(t + 2) * kstep;
;             const char* a3 = a2 + kstep; const char* b3 = b2 + kstep;
;             if (last && has_next) S.a_ready(nxt);
;             if constexpr (SP2) {
;             PG8_LDB(B0, 0, 0); PG8_LDB(B1, 0, 1); PG8_SCHED; PG8_LDA(At, 0, 0); PG8_STAGE(PG8_SA(1, 1), a1 + hstep, voffA);
;             PG8_WAIT_V(8); PG8_WAIT_L(0); PG8_BAR; PG8_MMAF(0, 0, At, B0); PG8_MMAF(0, 1, At, B1); PG8_BAR; PG8_SCHED;
;             const bool fin = last && !has_next;
;             PG8_LDA(At, 0, 1); if (!fin) { PG8_STAGE(PG8_SB(0, 0), b2, voffB); PG8_STAGE(PG8_SB(0, 1), b2 + hstep, voffB); PG8_STAGE(PG8_SA(0, 0), a2, voffA); }
;             if (!fin) PG8_WAIT_V(8); else PG8_WAIT_V(2); PG8_WAIT_L(0); PG8_BAR; PG8_MMAF(1, 0, At, B0); PG8_MMAF(1, 1, At, B1); PG8_BAR; PG8_SCHED;
;             PG8_LDB(B0, 1, 0); PG8_LDB(B1, 1, 1); PG8_SCHED; PG8_LDA(At, 1, 0); if (!fin) PG8_STAGE(PG8_SA(0, 1), a2 + hstep, voffA);
;             if (!fin) PG8_WAIT_V(8); else PG8_WAIT_V(0); PG8_WAIT_L(0); PG8_BAR; PG8_MMA(0, 0, At, B0); PG8_MMA(0, 1, At, B1); PG8_BAR; PG8_SCHED;
;             PG8_LDA(At, 1, 1); if (!fin) { PG8_STAGE(PG8_SB(1, 0), b3, voffB); PG8_STAGE(PG8_SB(1, 1), b3 + hstep, voffB); PG8_STAGE(PG8_SA(1, 0), a3, voffA); }
;             if (!fin) PG8_WAIT_V(8); PG8_WAIT_L(0); PG8_BAR; PG8_MMA(1, 0, At, B0); PG8_MMA(1, 1, At, B1); PG8_BAR; PG8_SCHED;
.LBB0_988:
	s_waitcnt lgkmcnt(0)
	s_barrier
	v_mfma_f32_16x16x32_f16 v[62:65], v[166:169], v[186:189], v[62:65]
	s_setprio 1
	v_mfma_f32_16x16x32_f16 v[62:65], v[170:173], v[190:193], v[62:65]
	v_mfma_f32_16x16x32_f16 v[58:61], v[158:161], v[186:189], v[58:61]
	v_mfma_f32_16x16x32_f16 v[58:61], v[162:165], v[190:193], v[58:61]
	v_mfma_f32_16x16x32_f16 v[46:49], v[166:169], v[178:181], v[46:49]
	v_mfma_f32_16x16x32_f16 v[46:49], v[170:173], v[182:185], v[46:49]
	v_mfma_f32_16x16x32_f16 v[42:45], v[158:161], v[178:181], v[42:45]
	v_mfma_f32_16x16x32_f16 v[42:45], v[162:165], v[182:185], v[42:45]
	v_mfma_f32_16x16x32_f16 v[30:33], v[166:169], v[138:141], v[30:33]
	v_mfma_f32_16x16x32_f16 v[30:33], v[170:173], v[174:177], v[30:33]
	v_mfma_f32_16x16x32_f16 v[26:29], v[158:161], v[138:141], v[26:29]
	v_mfma_f32_16x16x32_f16 v[26:29], v[162:165], v[174:177], v[26:29]
	v_mfma_f32_16x16x32_f16 v[14:17], v[166:169], v[114:117], v[14:17]
	v_mfma_f32_16x16x32_f16 v[14:17], v[170:173], v[126:129], v[14:17]
	v_mfma_f32_16x16x32_f16 v[10:13], v[158:161], v[114:117], v[10:13]
	v_mfma_f32_16x16x32_f16 v[10:13], v[162:165], v[126:129], v[10:13]
	v_mfma_f32_16x16x32_f16 v[54:57], v[90:93], v[186:189], v[54:57]
	v_mfma_f32_16x16x32_f16 v[54:57], v[102:105], v[190:193], v[54:57]
	v_mfma_f32_16x16x32_f16 v[50:53], v[66:69], v[186:189], v[50:53]
	v_mfma_f32_16x16x32_f16 v[50:53], v[78:81], v[190:193], v[50:53]
	v_mfma_f32_16x16x32_f16 v[38:41], v[90:93], v[178:181], v[38:41]
	v_mfma_f32_16x16x32_f16 v[38:41], v[102:105], v[182:185], v[38:41]
	v_mfma_f32_16x16x32_f16 v[34:37], v[66:69], v[178:181], v[34:37]
	v_mfma_f32_16x16x32_f16 v[34:37], v[78:81], v[182:185], v[34:37]
	v_mfma_f32_16x16x32_f16 v[22:25], v[90:93], v[138:141], v[22:25]
	v_mfma_f32_16x16x32_f16 v[22:25], v[102:105], v[174:177], v[22:25]
	v_mfma_f32_16x16x32_f16 v[18:21], v[66:69], v[138:141], v[18:21]
	v_mfma_f32_16x16x32_f16 v[18:21], v[78:81], v[174:177], v[18:21]
	v_mfma_f32_16x16x32_f16 v[6:9], v[90:93], v[114:117], v[6:9]
	v_mfma_f32_16x16x32_f16 v[6:9], v[102:105], v[126:129], v[6:9]
	v_mfma_f32_16x16x32_f16 v[2:5], v[66:69], v[114:117], v[2:5]
	v_mfma_f32_16x16x32_f16 v[2:5], v[78:81], v[126:129], v[2:5]
	s_barrier
	s_setprio 0
	s_add_i32 s54, s54, 2
	s_add_u32 s52, s52, 0x100
	s_addc_u32 s53, s53, 0
	s_cmp_gt_u32 s54, 41
	s_cbranch_scc1 .LBB0_999

; #define PG8_STAGE(bufoff, gbase, voff) do { if constexpr (ABL & 1) break; glds16s<(bufoff)>((voff)[0], (const void*)(gbase), ldsbw); glds16s<(bufoff) + 8192>((voff)[1], (const void*)(gbase), ldsbw); } while (0)
; #define PG8_LDA(dst, b, h) do { if constexpr (ABL & 4) break; _Pragma("unroll") for (int m = 0; m < 4; ++m) _Pragma("unroll") for (int k = 0; k < 2; ++k) dst[m][k] = *(const LAS f16x8*)(lds + PG8_SA(b, h) + aoff + m * 2048 + k * 1024); } while (0)
; #define PG8_LDB(dst, b, h) do { if constexpr (ABL & 4) break; _Pragma("unroll") for (int n = 0; n < 2; ++n) _Pragma("unroll") for (int k = 0; k < 2; ++k) dst[n][k] = *(const LAS f16x8*)(lds + PG8_SB(b, h) + boff + n * 2048 + k * 1024); } while (0)
; #define PG8_MMA(ai, bj, At, Bt) do { if constexpr (ABL & 2) break; __builtin_amdgcn_s_setprio(1); _Pragma("unroll") for (int m = 0; m < 4; ++m) _Pragma("unroll") for (int n = 0; n < 2; ++n) _Pragma("unroll") for (int k = 0; k < 2; ++k) \
;         acc[ai][bj][m][n] = __builtin_amdgcn_mfma_f32_16x16x32_f16(Bt[n][k], At[m][k], acc[ai][bj][m][n], 0, 0, 0); __builtin_amdgcn_s_setprio(0); } while (0)
; #define PG8_MMAF(ai, bj, At, Bt) do { if (t == 0) PG8_MMA0(ai, bj, At, Bt); else PG8_MMA(ai, bj, At, Bt); } while (0)
; #define PG8_WAIT_V(n) asm volatile("s_waitcnt vmcnt(" #n ")" ::: "memory")
; #define PG8_WAIT_L(n) asm volatile("s_waitcnt lgkmcnt(" #n ")" ::: "memory")
; #define PG8_BAR __builtin_amdgcn_s_barrier()
; #define PG8_SCHED __builtin_amdgcn_sched_barrier(0)
;     ...
;             if (!fin) PG8_WAIT_V(8); else PG8_WAIT_V(2); PG8_WAIT_L(0); PG8_BAR; PG8_MMAF(1, 0, At, B0); PG8_MMAF(1, 1, At, B1); PG8_BAR; PG8_SCHED;
;             PG8_LDB(B0, 1, 0); PG8_LDB(B1, 1, 1); PG8_SCHED; PG8_LDA(At, 1, 0); if (!fin) PG8_STAGE(PG8_SA(0, 1), a2 + hstep, voffA);
;             if (!fin) PG8_WAIT_V(8); else PG8_WAIT_V(0); PG8_WAIT_L(0); PG8_BAR; PG8_MMA(0, 0, At, B0); PG8_MMA(0, 1, At, B1); PG8_BAR; PG8_SCHED;
.LBB0_993:
	s_waitcnt lgkmcnt(0)
	s_xor_b64 s[26:27], s[6:7], -1
	s_barrier
	v_mfma_f32_16x16x32_f16 v[62:65], v[158:161], v[186:189], v[62:65]
	s_setprio 1
	v_mfma_f32_16x16x32_f16 v[62:65], v[162:165], v[190:193], v[62:65]
	v_mfma_f32_16x16x32_f16 v[58:61], v[166:169], v[186:189], v[58:61]
	v_mfma_f32_16x16x32_f16 v[58:61], v[170:173], v[190:193], v[58:61]
	v_mfma_f32_16x16x32_f16 v[46:49], v[158:161], v[178:181], v[46:49]
	v_mfma_f32_16x16x32_f16 v[46:49], v[162:165], v[182:185], v[46:49]
	v_mfma_f32_16x16x32_f16 v[42:45], v[166:169], v[178:181], v[42:45]
	v_mfma_f32_16x16x32_f16 v[42:45], v[170:173], v[182:185], v[42:45]
	v_mfma_f32_16x16x32_f16 v[30:33], v[158:161], v[154:157], v[30:33]
	v_mfma_f32_16x16x32_f16 v[30:33], v[162:165], v[174:177], v[30:33]
	v_mfma_f32_16x16x32_f16 v[26:29], v[166:169], v[154:157], v[26:29]
	v_mfma_f32_16x16x32_f16 v[26:29], v[170:173], v[174:177], v[26:29]
	v_mfma_f32_16x16x32_f16 v[14:17], v[158:161], v[146:149], v[14:17]
	v_mfma_f32_16x16x32_f16 v[14:17], v[162:165], v[150:153], v[14:17]
	v_mfma_f32_16x16x32_f16 v[10:13], v[166:169], v[146:149], v[10:13]
	v_mfma_f32_16x16x32_f16 v[10:13], v[170:173], v[150:153], v[10:13]
	v_mfma_f32_16x16x32_f16 v[54:57], v[66:69], v[186:189], v[54:57]
	v_mfma_f32_16x16x32_f16 v[54:57], v[78:81], v[190:193], v[54:57]
	v_mfma_f32_16x16x32_f16 v[50:53], v[90:93], v[186:189], v[50:53]
	v_mfma_f32_16x16x32_f16 v[50:53], v[102:105], v[190:193], v[50:53]
	v_mfma_f32_16x16x32_f16 v[38:41], v[66:69], v[178:181], v[38:41]
	v_mfma_f32_16x16x32_f16 v[38:41], v[78:81], v[182:185], v[38:41]
	v_mfma_f32_16x16x32_f16 v[34:37], v[90:93], v[178:181], v[34:37]
	v_mfma_f32_16x16x32_f16 v[34:37], v[102:105], v[182:185], v[34:37]
	v_mfma_f32_16x16x32_f16 v[22:25], v[66:69], v[154:157], v[22:25]
	v_mfma_f32_16x16x32_f16 v[22:25], v[78:81], v[174:177], v[22:25]
	v_mfma_f32_16x16x32_f16 v[18:21], v[90:93], v[154:157], v[18:21]
	v_mfma_f32_16x16x32_f16 v[18:21], v[102:105], v[174:177], v[18:21]
	v_mfma_f32_16x16x32_f16 v[6:9], v[66:69], v[146:149], v[6:9]
	v_mfma_f32_16x16x32_f16 v[6:9], v[78:81], v[150:153], v[6:9]
	v_mfma_f32_16x16x32_f16 v[2:5], v[90:93], v[146:149], v[2:5]
	v_mfma_f32_16x16x32_f16 v[2:5], v[102:105], v[150:153], v[2:5]
	s_barrier
	s_setprio 0
	ds_read_b128 v[166:169], v216
	ds_read_b128 v[170:173], v216 offset:1024
	ds_read_b128 v[158:161], v216 offset:2048
	ds_read_b128 v[162:165], v216 offset:3072
	ds_read_b128 v[90:93], v217
	ds_read_b128 v[102:105], v217 offset:1024
	ds_read_b128 v[66:69], v217 offset:2048
	ds_read_b128 v[78:81], v217 offset:3072
	ds_read_b128 v[198:201], v215 offset:32768
	ds_read_b128 v[202:205], v215 offset:33792
	ds_read_b128 v[190:193], v215 offset:34816
	ds_read_b128 v[194:197], v215 offset:35840
	ds_read_b128 v[182:185], v215 offset:36864
	ds_read_b128 v[186:189], v215 offset:37888
	ds_read_b128 v[174:177], v215 offset:38912
	ds_read_b128 v[178:181], v215 offset:39936
	v_cndmask_b32_e64 v146, 0, 1, s[26:27]
	v_cmp_ne_u32_e64 s[6:7], 1, v146
	s_andn2_b64 vcc, exec, s[26:27]
	s_mov_b64 s[26:27], -1
	s_cbranch_vccnz .LBB0_995
	s_add_u32 s26, s24, 0xb0000
	s_addc_u32 s27, s25, 0
	s_add_u32 m0, s28, 0x4000
	s_nop 0
	global_load_lds_dwordx4 v1, s[26:27]
	s_nop 0
	s_add_u32 m0, s28, 0x6000
	s_nop 0
	global_load_lds_dwordx4 v211, s[26:27]
	s_waitcnt vmcnt(8)
	s_mov_b64 s[26:27], 0

; #define PG8_STAGE(bufoff, gbase, voff) do { if constexpr (ABL & 1) break; glds16s<(bufoff)>((voff)[0], (const void*)(gbase), ldsbw); glds16s<(bufoff) + 8192>((voff)[1], (const void*)(gbase), ldsbw); } while (0)
; #define PG8_LDA(dst, b, h) do { if constexpr (ABL & 4) break; _Pragma("unroll") for (int m = 0; m < 4; ++m) _Pragma("unroll") for (int k = 0; k < 2; ++k) dst[m][k] = *(const LAS f16x8*)(lds + PG8_SA(b, h) + aoff + m * 2048 + k * 1024); } while (0)
; #define PG8_LDB(dst, b, h) do { if constexpr (ABL & 4) break; _Pragma("unroll") for (int n = 0; n < 2; ++n) _Pragma("unroll") for (int k = 0; k < 2; ++k) dst[n][k] = *(const LAS f16x8*)(lds + PG8_SB(b, h) + boff + n * 2048 + k * 1024); } while (0)
; #define PG8_BAR __builtin_amdgcn_s_barrier()
;     ...
;         for (int t = 0; t < nt; t += 2) {
;             const bool last = (t == nt - 2);
;             const char* a1 = cA + (size_t)(t + 1) * kstep;
;             const char* a2 = last ? nA : cA + (size_t)(t + 2) * kstep; const char* b2 = last ? nB : cB + (size_t)(t + 2) * kstep;
;             const char* a3 = a2 + kstep; const char* b3 = b2 + kstep;
;             if (last && has_next) S.a_ready(nxt);
;             if constexpr (SP2) {
;             PG8_LDB(B0, 0, 0); PG8_LDB(B1, 0, 1); PG8_SCHED; PG8_LDA(At, 0, 0); PG8_STAGE(PG8_SA(1, 1), a1 + hstep, voffA);
;             PG8_WAIT_V(8); PG8_WAIT_L(0); PG8_BAR; PG8_MMAF(0, 0, At, B0); PG8_MMAF(0, 1, At, B1); PG8_BAR; PG8_SCHED;
;             const bool fin = last && !has_next;
;             PG8_LDA(At, 0, 1); if (!fin) { PG8_STAGE(PG8_SB(0, 0), b2, voffB); PG8_STAGE(PG8_SB(0, 1), b2 + hstep, voffB); PG8_STAGE(PG8_SA(0, 0), a2, voffA); }
;             if (!fin) PG8_WAIT_V(8); else PG8_WAIT_V(2); PG8_WAIT_L(0); PG8_BAR; PG8_MMAF(1, 0, At, B0); PG8_MMAF(1, 1, At, B1); PG8_BAR; PG8_SCHED;
;             PG8_LDB(B0, 1, 0); PG8_LDB(B1, 1, 1); PG8_SCHED; PG8_LDA(At, 1, 0); if (!fin) PG8_STAGE(PG8_SA(0, 1), a2 + hstep, voffA);
;             if (!fin) PG8_WAIT_V(8); else PG8_WAIT_V(0); PG8_WAIT_L(0); PG8_BAR; PG8_MMA(0, 0, At, B0); PG8_MMA(0, 1, At, B1); PG8_BAR; PG8_SCHED;
;             PG8_LDA(At, 1, 1); if (!fin) { PG8_STAGE(PG8_SB(1, 0), b3, voffB); PG8_STAGE(PG8_SB(1, 1), b3 + hstep, voffB); PG8_STAGE(PG8_SA(1, 0), a3, voffA); }
;             if (!fin) PG8_WAIT_V(8); PG8_WAIT_L(0); PG8_BAR; PG8_MMA(1, 0, At, B0); PG8_MMA(1, 1, At, B1); PG8_BAR; PG8_SCHED;
.LBB0_1112:
	s_waitcnt lgkmcnt(0)
	s_barrier
	v_mfma_f32_16x16x32_f16 v[62:65], v[146:149], v[186:189], v[62:65]
	s_setprio 1
	v_mfma_f32_16x16x32_f16 v[62:65], v[150:153], v[190:193], v[62:65]
	v_mfma_f32_16x16x32_f16 v[58:61], v[154:157], v[186:189], v[58:61]
	v_mfma_f32_16x16x32_f16 v[58:61], v[158:161], v[190:193], v[58:61]
	v_mfma_f32_16x16x32_f16 v[46:49], v[146:149], v[178:181], v[46:49]
	v_mfma_f32_16x16x32_f16 v[46:49], v[150:153], v[182:185], v[46:49]
	v_mfma_f32_16x16x32_f16 v[42:45], v[154:157], v[178:181], v[42:45]
	v_mfma_f32_16x16x32_f16 v[42:45], v[158:161], v[182:185], v[42:45]
	v_mfma_f32_16x16x32_f16 v[30:33], v[146:149], v[170:173], v[30:33]
	v_mfma_f32_16x16x32_f16 v[30:33], v[150:153], v[174:177], v[30:33]
	v_mfma_f32_16x16x32_f16 v[26:29], v[154:157], v[170:173], v[26:29]
	v_mfma_f32_16x16x32_f16 v[26:29], v[158:161], v[174:177], v[26:29]
	v_mfma_f32_16x16x32_f16 v[14:17], v[146:149], v[162:165], v[14:17]
	v_mfma_f32_16x16x32_f16 v[14:17], v[150:153], v[166:169], v[14:17]
	v_mfma_f32_16x16x32_f16 v[10:13], v[154:157], v[162:165], v[10:13]
	v_mfma_f32_16x16x32_f16 v[10:13], v[158:161], v[166:169], v[10:13]
	v_mfma_f32_16x16x32_f16 v[54:57], v[130:133], v[186:189], v[54:57]
	v_mfma_f32_16x16x32_f16 v[54:57], v[134:137], v[190:193], v[54:57]
	v_mfma_f32_16x16x32_f16 v[50:53], v[138:141], v[186:189], v[50:53]
	v_mfma_f32_16x16x32_f16 v[50:53], v[142:145], v[190:193], v[50:53]
	v_mfma_f32_16x16x32_f16 v[38:41], v[130:133], v[178:181], v[38:41]
	v_mfma_f32_16x16x32_f16 v[38:41], v[134:137], v[182:185], v[38:41]
	v_mfma_f32_16x16x32_f16 v[34:37], v[138:141], v[178:181], v[34:37]
	v_mfma_f32_16x16x32_f16 v[34:37], v[142:145], v[182:185], v[34:37]
	v_mfma_f32_16x16x32_f16 v[22:25], v[130:133], v[170:173], v[22:25]
	v_mfma_f32_16x16x32_f16 v[22:25], v[134:137], v[174:177], v[22:25]
	v_mfma_f32_16x16x32_f16 v[18:21], v[138:141], v[170:173], v[18:21]
	v_mfma_f32_16x16x32_f16 v[18:21], v[142:145], v[174:177], v[18:21]
	v_mfma_f32_16x16x32_f16 v[6:9], v[130:133], v[162:165], v[6:9]
	v_mfma_f32_16x16x32_f16 v[6:9], v[134:137], v[166:169], v[6:9]
	v_mfma_f32_16x16x32_f16 v[2:5], v[138:141], v[162:165], v[2:5]
	v_mfma_f32_16x16x32_f16 v[2:5], v[142:145], v[166:169], v[2:5]
	s_barrier
	s_setprio 0
	s_add_i32 s58, s58, 2
	s_add_u32 s54, s54, 0x100
	s_addc_u32 s55, s55, 0
	s_cmp_gt_u32 s58, 13
	s_cbranch_scc1 .LBB0_1123
.LBB0_1113:
	ds_read_b128 v[146:149], v201
	ds_read_b128 v[150:153], v201 offset:1024
	ds_read_b128 v[154:157], v201 offset:2048
	ds_read_b128 v[158:161], v201 offset:3072
	ds_read_b128 v[130:133], v202
	ds_read_b128 v[134:137], v202 offset:1024
	ds_read_b128 v[138:141], v202 offset:2048
	ds_read_b128 v[142:145], v202 offset:3072
	s_mov_b64 s[6:7], s[52:53]
	s_add_u32 s52, s6, 0x100
	s_addc_u32 s53, s7, 0
	s_cmp_eq_u32 s58, 12
	s_cselect_b64 s[26:27], -1, 0
	s_and_b64 s[8:9], s[26:27], exec
	s_cselect_b32 s25, s43, s53
	s_cselect_b32 s24, s56, s52
	s_cselect_b32 s9, s41, s55
	s_cselect_b32 s8, s57, s54
	ds_read_b128 v[162:165], v203
	ds_read_b128 v[166:169], v203 offset:1024
	ds_read_b128 v[170:173], v203 offset:2048
	ds_read_b128 v[174:177], v203 offset:3072
	ds_read_b128 v[178:181], v203 offset:4096
	ds_read_b128 v[182:185], v203 offset:5120
	ds_read_b128 v[186:189], v203 offset:6144
	ds_read_b128 v[190:193], v203 offset:7168
	s_add_u32 s6, s6, 0x40080
	s_addc_u32 s7, s7, 0
	s_add_u32 m0, s28, 0xc000
	s_nop 0
	global_load_lds_dwordx4 v1, s[6:7]
	s_nop 0
	s_add_u32 m0, s28, 0xe000
	s_nop 0
	global_load_lds_dwordx4 v199, s[6:7]
	s_waitcnt vmcnt(8)
	s_waitcnt lgkmcnt(0)
	s_barrier
	v_mfma_f32_16x16x32_f16 v[126:129], v[146:149], v[162:165], v[126:129]
	s_setprio 1
	v_mfma_f32_16x16x32_f16 v[126:129], v[150:153], v[166:169], v[126:129]
	v_mfma_f32_16x16x32_f16 v[122:125], v[154:157], v[162:165], v[122:125]
	v_mfma_f32_16x16x32_f16 v[122:125], v[158:161], v[166:169], v[122:125]
	v_mfma_f32_16x16x32_f16 v[110:113], v[146:149], v[170:173], v[110:113]
	v_mfma_f32_16x16x32_f16 v[110:113], v[150:153], v[174:177], v[110:113]
	v_mfma_f32_16x16x32_f16 v[106:109], v[154:157], v[170:173], v[106:109]
	v_mfma_f32_16x16x32_f16 v[106:109], v[158:161], v[174:177], v[106:109]
	v_mfma_f32_16x16x32_f16 v[94:97], v[146:149], v[178:181], v[94:97]
	v_mfma_f32_16x16x32_f16 v[94:97], v[150:153], v[182:185], v[94:97]
	v_mfma_f32_16x16x32_f16 v[90:93], v[154:157], v[178:181], v[90:93]
	v_mfma_f32_16x16x32_f16 v[90:93], v[158:161], v[182:185], v[90:93]
	v_mfma_f32_16x16x32_f16 v[78:81], v[146:149], v[186:189], v[78:81]
	v_mfma_f32_16x16x32_f16 v[78:81], v[150:153], v[190:193], v[78:81]
	v_mfma_f32_16x16x32_f16 v[74:77], v[154:157], v[186:189], v[74:77]
	v_mfma_f32_16x16x32_f16 v[74:77], v[158:161], v[190:193], v[74:77]
	v_mfma_f32_16x16x32_f16 v[118:121], v[130:133], v[162:165], v[118:121]
	v_mfma_f32_16x16x32_f16 v[118:121], v[134:137], v[166:169], v[118:121]
	v_mfma_f32_16x16x32_f16 v[114:117], v[138:141], v[162:165], v[114:117]
	v_mfma_f32_16x16x32_f16 v[114:117], v[142:145], v[166:169], v[114:117]
	v_mfma_f32_16x16x32_f16 v[102:105], v[130:133], v[170:173], v[102:105]
	v_mfma_f32_16x16x32_f16 v[102:105], v[134:137], v[174:177], v[102:105]
	v_mfma_f32_16x16x32_f16 v[98:101], v[138:141], v[170:173], v[98:101]
	v_mfma_f32_16x16x32_f16 v[98:101], v[142:145], v[174:177], v[98:101]
	v_mfma_f32_16x16x32_f16 v[86:89], v[130:133], v[178:181], v[86:89]
	v_mfma_f32_16x16x32_f16 v[86:89], v[134:137], v[182:185], v[86:89]
	v_mfma_f32_16x16x32_f16 v[82:85], v[138:141], v[178:181], v[82:85]
	v_mfma_f32_16x16x32_f16 v[82:85], v[142:145], v[182:185], v[82:85]
	v_mfma_f32_16x16x32_f16 v[70:73], v[130:133], v[186:189], v[70:73]
	v_mfma_f32_16x16x32_f16 v[70:73], v[134:137], v[190:193], v[70:73]
	v_mfma_f32_16x16x32_f16 v[66:69], v[138:141], v[186:189], v[66:69]
	v_mfma_f32_16x16x32_f16 v[66:69], v[142:145], v[190:193], v[66:69]
	s_barrier
	s_setprio 0
	ds_read_b128 v[186:189], v203 offset:16384
	ds_read_b128 v[190:193], v203 offset:17408
	ds_read_b128 v[178:181], v203 offset:18432
	ds_read_b128 v[182:185], v203 offset:19456
	ds_read_b128 v[170:173], v203 offset:20480
	ds_read_b128 v[174:177], v203 offset:21504
	ds_read_b128 v[162:165], v203 offset:22528
	ds_read_b128 v[166:169], v203 offset:23552
	s_and_b64 s[6:7], s[4:5], s[26:27]
	s_mov_b64 s[26:27], -1
	s_and_b64 vcc, exec, s[6:7]
	s_cbranch_vccnz .LBB0_1115
	s_add_u32 m0, s28, 0x10000
	s_nop 0
	global_load_lds_dwordx4 v198, s[8:9]
	s_nop 0
	s_add_u32 m0, s28, 0x12000
	s_nop 0
	global_load_lds_dwordx4 v200, s[8:9]
	s_add_u32 s26, s8, 0x40000
	s_addc_u32 s27, s9, 0
	s_add_u32 m0, s28, 0x14000
	s_nop 0
	global_load_lds_dwordx4 v198, s[26:27]
	s_nop 0
	s_add_u32 m0, s28, 0x16000
	s_nop 0
	global_load_lds_dwordx4 v200, s[26:27]
	s_mov_b64 s[26:27], 0
	s_add_u32 m0, s28, 0
	s_nop 0
	global_load_lds_dwordx4 v1, s[24:25]
	s_nop 0
	s_add_u32 m0, s28, 0x2000
	s_nop 0
	global_load_lds_dwordx4 v199, s[24:25]
	s_waitcnt vmcnt(8)

; #define PG8_STAGE(bufoff, gbase, voff) do { if constexpr (ABL & 1) break; glds16s<(bufoff)>((voff)[0], (const void*)(gbase), ldsbw); glds16s<(bufoff) + 8192>((voff)[1], (const void*)(gbase), ldsbw); } while (0)
; #define PG8_LDA(dst, b, h) do { if constexpr (ABL & 4) break; _Pragma("unroll") for (int m = 0; m < 4; ++m) _Pragma("unroll") for (int k = 0; k < 2; ++k) dst[m][k] = *(const LAS f16x8*)(lds + PG8_SA(b, h) + aoff + m * 2048 + k * 1024); } while (0)
; #define PG8_LDB(dst, b, h) do { if constexpr (ABL & 4) break; _Pragma("unroll") for (int n = 0; n < 2; ++n) _Pragma("unroll") for (int k = 0; k < 2; ++k) dst[n][k] = *(const LAS f16x8*)(lds + PG8_SB(b, h) + boff + n * 2048 + k * 1024); } while (0)
; #define PG8_MMA(ai, bj, At, Bt) do { if constexpr (ABL & 2) break; __builtin_amdgcn_s_setprio(1); _Pragma("unroll") for (int m = 0; m < 4; ++m) _Pragma("unroll") for (int n = 0; n < 2; ++n) _Pragma("unroll") for (int k = 0; k < 2; ++k) \
;         acc[ai][bj][m][n] = __builtin_amdgcn_mfma_f32_16x16x32_f16(Bt[n][k], At[m][k], acc[ai][bj][m][n], 0, 0, 0); __builtin_amdgcn_s_setprio(0); } while (0)
; #define PG8_MMAF(ai, bj, At, Bt) do { if (t == 0) PG8_MMA0(ai, bj, At, Bt); else PG8_MMA(ai, bj, At, Bt); } while (0)
; #define PG8_WAIT_V(n) asm volatile("s_waitcnt vmcnt(" #n ")" ::: "memory")
; #define PG8_WAIT_L(n) asm volatile("s_waitcnt lgkmcnt(" #n ")" ::: "memory")
; #define PG8_BAR __builtin_amdgcn_s_barrier()
; #define PG8_SCHED __builtin_amdgcn_sched_barrier(0)
;     ...
;             if (!fin) PG8_WAIT_V(8); else PG8_WAIT_V(2); PG8_WAIT_L(0); PG8_BAR; PG8_MMAF(1, 0, At, B0); PG8_MMAF(1, 1, At, B1); PG8_BAR; PG8_SCHED;
;             PG8_LDB(B0, 1, 0); PG8_LDB(B1, 1, 1); PG8_SCHED; PG8_LDA(At, 1, 0); if (!fin) PG8_STAGE(PG8_SA(0, 1), a2 + hstep, voffA);
;             if (!fin) PG8_WAIT_V(8); else PG8_WAIT_V(0); PG8_WAIT_L(0); PG8_BAR; PG8_MMA(0, 0, At, B0); PG8_MMA(0, 1, At, B1); PG8_BAR; PG8_SCHED;
.LBB0_1117:
	s_waitcnt lgkmcnt(0)
	s_xor_b64 s[26:27], s[6:7], -1
	s_barrier
	v_mfma_f32_16x16x32_f16 v[62:65], v[146:149], v[186:189], v[62:65]
	s_setprio 1
	v_mfma_f32_16x16x32_f16 v[62:65], v[150:153], v[190:193], v[62:65]
	v_mfma_f32_16x16x32_f16 v[58:61], v[154:157], v[186:189], v[58:61]
	v_mfma_f32_16x16x32_f16 v[58:61], v[158:161], v[190:193], v[58:61]
	v_mfma_f32_16x16x32_f16 v[46:49], v[146:149], v[178:181], v[46:49]
	v_mfma_f32_16x16x32_f16 v[46:49], v[150:153], v[182:185], v[46:49]
	v_mfma_f32_16x16x32_f16 v[42:45], v[154:157], v[178:181], v[42:45]
	v_mfma_f32_16x16x32_f16 v[42:45], v[158:161], v[182:185], v[42:45]
	v_mfma_f32_16x16x32_f16 v[30:33], v[146:149], v[170:173], v[30:33]
	v_mfma_f32_16x16x32_f16 v[30:33], v[150:153], v[174:177], v[30:33]
	v_mfma_f32_16x16x32_f16 v[26:29], v[154:157], v[170:173], v[26:29]
	v_mfma_f32_16x16x32_f16 v[26:29], v[158:161], v[174:177], v[26:29]
	v_mfma_f32_16x16x32_f16 v[14:17], v[146:149], v[162:165], v[14:17]
	v_mfma_f32_16x16x32_f16 v[14:17], v[150:153], v[166:169], v[14:17]
	v_mfma_f32_16x16x32_f16 v[10:13], v[154:157], v[162:165], v[10:13]
	v_mfma_f32_16x16x32_f16 v[10:13], v[158:161], v[166:169], v[10:13]
	v_mfma_f32_16x16x32_f16 v[54:57], v[130:133], v[186:189], v[54:57]
	v_mfma_f32_16x16x32_f16 v[54:57], v[134:137], v[190:193], v[54:57]
	v_mfma_f32_16x16x32_f16 v[50:53], v[138:141], v[186:189], v[50:53]
	v_mfma_f32_16x16x32_f16 v[50:53], v[142:145], v[190:193], v[50:53]
	v_mfma_f32_16x16x32_f16 v[38:41], v[130:133], v[178:181], v[38:41]
	v_mfma_f32_16x16x32_f16 v[38:41], v[134:137], v[182:185], v[38:41]
	v_mfma_f32_16x16x32_f16 v[34:37], v[138:141], v[178:181], v[34:37]
	v_mfma_f32_16x16x32_f16 v[34:37], v[142:145], v[182:185], v[34:37]
	v_mfma_f32_16x16x32_f16 v[22:25], v[130:133], v[170:173], v[22:25]
	v_mfma_f32_16x16x32_f16 v[22:25], v[134:137], v[174:177], v[22:25]
	v_mfma_f32_16x16x32_f16 v[18:21], v[138:141], v[170:173], v[18:21]
	v_mfma_f32_16x16x32_f16 v[18:21], v[142:145], v[174:177], v[18:21]
	v_mfma_f32_16x16x32_f16 v[6:9], v[130:133], v[162:165], v[6:9]
	v_mfma_f32_16x16x32_f16 v[6:9], v[134:137], v[166:169], v[6:9]
	v_mfma_f32_16x16x32_f16 v[2:5], v[138:141], v[162:165], v[2:5]
	v_mfma_f32_16x16x32_f16 v[2:5], v[142:145], v[166:169], v[2:5]
	s_barrier
	s_setprio 0
	ds_read_b128 v[146:149], v204
	ds_read_b128 v[150:153], v204 offset:1024
	ds_read_b128 v[154:157], v204 offset:2048
	ds_read_b128 v[158:161], v204 offset:3072
	ds_read_b128 v[130:133], v205
	ds_read_b128 v[134:137], v205 offset:1024
	ds_read_b128 v[138:141], v205 offset:2048
	ds_read_b128 v[142:145], v205 offset:3072
	ds_read_b128 v[186:189], v203 offset:32768
	ds_read_b128 v[190:193], v203 offset:33792
	ds_read_b128 v[178:181], v203 offset:34816
	ds_read_b128 v[182:185], v203 offset:35840
	ds_read_b128 v[170:173], v203 offset:36864
	ds_read_b128 v[174:177], v203 offset:37888
	ds_read_b128 v[162:165], v203 offset:38912
	ds_read_b128 v[166:169], v203 offset:39936
	v_cndmask_b32_e64 v209, 0, 1, s[26:27]
	v_cmp_ne_u32_e64 s[6:7], 1, v209
	s_andn2_b64 vcc, exec, s[26:27]
	s_mov_b64 s[26:27], -1
	s_cbranch_vccnz .LBB0_1119
	s_add_u32 s26, s24, 0x40000
	s_addc_u32 s27, s25, 0
	s_add_u32 m0, s28, 0x4000
	s_nop 0
	global_load_lds_dwordx4 v1, s[26:27]
	s_nop 0
	s_add_u32 m0, s28, 0x6000
	s_nop 0
	global_load_lds_dwordx4 v199, s[26:27]
	s_waitcnt vmcnt(8)
	s_mov_b64 s[26:27], 0

; #define PG8_STAGE(bufoff, gbase, voff) do { if constexpr (ABL & 1) break; glds16s<(bufoff)>((voff)[0], (const void*)(gbase), ldsbw); glds16s<(bufoff) + 8192>((voff)[1], (const void*)(gbase), ldsbw); } while (0)
; #define PG8_LDA(dst, b, h) do { if constexpr (ABL & 4) break; _Pragma("unroll") for (int m = 0; m < 4; ++m) _Pragma("unroll") for (int k = 0; k < 2; ++k) dst[m][k] = *(const LAS f16x8*)(lds + PG8_SA(b, h) + aoff + m * 2048 + k * 1024); } while (0)
; #define PG8_MMA(ai, bj, At, Bt) do { if constexpr (ABL & 2) break; __builtin_amdgcn_s_setprio(1); _Pragma("unroll") for (int m = 0; m < 4; ++m) _Pragma("unroll") for (int n = 0; n < 2; ++n) _Pragma("unroll") for (int k = 0; k < 2; ++k) \
;         acc[ai][bj][m][n] = __builtin_amdgcn_mfma_f32_16x16x32_f16(Bt[n][k], At[m][k], acc[ai][bj][m][n], 0, 0, 0); __builtin_amdgcn_s_setprio(0); } while (0)
; #define PG8_WAIT_V(n) asm volatile("s_waitcnt vmcnt(" #n ")" ::: "memory")
; #define PG8_WAIT_L(n) asm volatile("s_waitcnt lgkmcnt(" #n ")" ::: "memory")
; #define PG8_BAR __builtin_amdgcn_s_barrier()
; #define PG8_SCHED __builtin_amdgcn_sched_barrier(0)
;     ...
;             if (!fin) PG8_WAIT_V(8); else PG8_WAIT_V(0); PG8_WAIT_L(0); PG8_BAR; PG8_MMA(0, 0, At, B0); PG8_MMA(0, 1, At, B1); PG8_BAR; PG8_SCHED;
;             PG8_LDA(At, 1, 1); if (!fin) { PG8_STAGE(PG8_SB(1, 0), b3, voffB); PG8_STAGE(PG8_SB(1, 1), b3 + hstep, voffB); PG8_STAGE(PG8_SA(1, 0), a3, voffA); }
;             if (!fin) PG8_WAIT_V(8); PG8_WAIT_L(0); PG8_BAR; PG8_MMA(1, 0, At, B0); PG8_MMA(1, 1, At, B1); PG8_BAR; PG8_SCHED;
.LBB0_1121:
	s_waitcnt lgkmcnt(0)
	s_barrier
	v_mfma_f32_16x16x32_f16 v[126:129], v[146:149], v[186:189], v[126:129]
	s_setprio 1
	v_mfma_f32_16x16x32_f16 v[126:129], v[150:153], v[190:193], v[126:129]
	v_mfma_f32_16x16x32_f16 v[122:125], v[154:157], v[186:189], v[122:125]
	v_mfma_f32_16x16x32_f16 v[122:125], v[158:161], v[190:193], v[122:125]
	v_mfma_f32_16x16x32_f16 v[110:113], v[146:149], v[178:181], v[110:113]
	v_mfma_f32_16x16x32_f16 v[110:113], v[150:153], v[182:185], v[110:113]
	v_mfma_f32_16x16x32_f16 v[106:109], v[154:157], v[178:181], v[106:109]
	v_mfma_f32_16x16x32_f16 v[106:109], v[158:161], v[182:185], v[106:109]
	v_mfma_f32_16x16x32_f16 v[94:97], v[146:149], v[170:173], v[94:97]
	v_mfma_f32_16x16x32_f16 v[94:97], v[150:153], v[174:177], v[94:97]
	v_mfma_f32_16x16x32_f16 v[90:93], v[154:157], v[170:173], v[90:93]
	v_mfma_f32_16x16x32_f16 v[90:93], v[158:161], v[174:177], v[90:93]
	v_mfma_f32_16x16x32_f16 v[78:81], v[146:149], v[162:165], v[78:81]
	v_mfma_f32_16x16x32_f16 v[78:81], v[150:153], v[166:169], v[78:81]
	v_mfma_f32_16x16x32_f16 v[74:77], v[154:157], v[162:165], v[74:77]
	v_mfma_f32_16x16x32_f16 v[74:77], v[158:161], v[166:169], v[74:77]
	v_mfma_f32_16x16x32_f16 v[118:121], v[130:133], v[186:189], v[118:121]
	v_mfma_f32_16x16x32_f16 v[118:121], v[134:137], v[190:193], v[118:121]
	v_mfma_f32_16x16x32_f16 v[114:117], v[138:141], v[186:189], v[114:117]
	v_mfma_f32_16x16x32_f16 v[114:117], v[142:145], v[190:193], v[114:117]
	v_mfma_f32_16x16x32_f16 v[102:105], v[130:133], v[178:181], v[102:105]
	v_mfma_f32_16x16x32_f16 v[102:105], v[134:137], v[182:185], v[102:105]
	v_mfma_f32_16x16x32_f16 v[98:101], v[138:141], v[178:181], v[98:101]
	v_mfma_f32_16x16x32_f16 v[98:101], v[142:145], v[182:185], v[98:101]
	v_mfma_f32_16x16x32_f16 v[86:89], v[130:133], v[170:173], v[86:89]
	v_mfma_f32_16x16x32_f16 v[86:89], v[134:137], v[174:177], v[86:89]
	v_mfma_f32_16x16x32_f16 v[82:85], v[138:141], v[170:173], v[82:85]
	v_mfma_f32_16x16x32_f16 v[82:85], v[142:145], v[174:177], v[82:85]
	v_mfma_f32_16x16x32_f16 v[70:73], v[130:133], v[162:165], v[70:73]
	v_mfma_f32_16x16x32_f16 v[70:73], v[134:137], v[166:169], v[70:73]
	v_mfma_f32_16x16x32_f16 v[66:69], v[138:141], v[162:165], v[66:69]
	v_mfma_f32_16x16x32_f16 v[66:69], v[142:145], v[166:169], v[66:69]
	s_barrier
	s_setprio 0
	ds_read_b128 v[186:189], v203 offset:49152
	ds_read_b128 v[190:193], v203 offset:50176
	ds_read_b128 v[178:181], v203 offset:51200
	ds_read_b128 v[182:185], v203 offset:52224
	ds_read_b128 v[170:173], v203 offset:53248
	ds_read_b128 v[174:177], v203 offset:54272
	ds_read_b128 v[162:165], v203 offset:55296
	ds_read_b128 v[166:169], v203 offset:56320
	s_and_b64 vcc, exec, s[6:7]
	s_cbranch_vccnz .LBB0_1112
	s_add_u32 s6, s24, 0x80
	s_addc_u32 s7, s25, 0
	s_add_u32 s24, s8, 0x80
	s_addc_u32 s25, s9, 0
	s_add_u32 m0, s28, 0x18000
	s_nop 0
	global_load_lds_dwordx4 v198, s[24:25]
	s_nop 0
	s_add_u32 m0, s28, 0x1a000
	s_nop 0
	global_load_lds_dwordx4 v200, s[24:25]
	s_add_u32 s8, s8, 0x40080
	s_addc_u32 s9, s9, 0
	s_add_u32 m0, s28, 0x1c000
	s_nop 0
	global_load_lds_dwordx4 v198, s[8:9]
	s_nop 0
	s_add_u32 m0, s28, 0x1e000
	s_nop 0
	global_load_lds_dwordx4 v200, s[8:9]
	s_nop 0
	s_add_u32 m0, s28, 0x8000
	s_nop 0
	global_load_lds_dwordx4 v1, s[6:7]
	s_nop 0
	s_add_u32 m0, s28, 0xa000
	s_nop 0
	global_load_lds_dwordx4 v199, s[6:7]
	s_waitcnt vmcnt(8)
	s_branch .LBB0_1112

; #define PG8_STAGE(bufoff, gbase, voff) do { if constexpr (ABL & 1) break; glds16s<(bufoff)>((voff)[0], (const void*)(gbase), ldsbw); glds16s<(bufoff) + 8192>((voff)[1], (const void*)(gbase), ldsbw); } while (0)
; #define PG8_LDA(dst, b, h) do { if constexpr (ABL & 4) break; _Pragma("unroll") for (int m = 0; m < 4; ++m) _Pragma("unroll") for (int k = 0; k < 2; ++k) dst[m][k] = *(const LAS f16x8*)(lds + PG8_SA(b, h) + aoff + m * 2048 + k * 1024); } while (0)
; #define PG8_LDB(dst, b, h) do { if constexpr (ABL & 4) break; _Pragma("unroll") for (int n = 0; n < 2; ++n) _Pragma("unroll") for (int k = 0; k < 2; ++k) dst[n][k] = *(const LAS f16x8*)(lds + PG8_SB(b, h) + boff + n * 2048 + k * 1024); } while (0)
; #define PG8_BAR __builtin_amdgcn_s_barrier()
;     ...
;         for (int t = 0; t < nt; t += 2) {
;             const bool last = (t == nt - 2);
;             const char* a1 = cA + (size_t)(t + 1) * kstep;
;             const char* a2 = last ? nA : cA + (size_t)(t + 2) * kstep; const char* b2 = last ? nB : cB + (size_t)(t + 2) * kstep;
;             const char* a3 = a2 + kstep; const char* b3 = b2 + kstep;
;             if (last && has_next) S.a_ready(nxt);
;             if constexpr (SP2) {
;             PG8_LDB(B0, 0, 0); PG8_LDB(B1, 0, 1); PG8_SCHED; PG8_LDA(At, 0, 0); PG8_STAGE(PG8_SA(1, 1), a1 + hstep, voffA);
;             PG8_WAIT_V(8); PG8_WAIT_L(0); PG8_BAR; PG8_MMAF(0, 0, At, B0); PG8_MMAF(0, 1, At, B1); PG8_BAR; PG8_SCHED;
;             const bool fin = last && !has_next;
;             PG8_LDA(At, 0, 1); if (!fin) { PG8_STAGE(PG8_SB(0, 0), b2, voffB); PG8_STAGE(PG8_SB(0, 1), b2 + hstep, voffB); PG8_STAGE(PG8_SA(0, 0), a2, voffA); }
;             if (!fin) PG8_WAIT_V(8); else PG8_WAIT_V(2); PG8_WAIT_L(0); PG8_BAR; PG8_MMAF(1, 0, At, B0); PG8_MMAF(1, 1, At, B1); PG8_BAR; PG8_SCHED;
;             PG8_LDB(B0, 1, 0); PG8_LDB(B1, 1, 1); PG8_SCHED; PG8_LDA(At, 1, 0); if (!fin) PG8_STAGE(PG8_SA(0, 1), a2 + hstep, voffA);
;             if (!fin) PG8_WAIT_V(8); else PG8_WAIT_V(0); PG8_WAIT_L(0); PG8_BAR; PG8_MMA(0, 0, At, B0); PG8_MMA(0, 1, At, B1); PG8_BAR; PG8_SCHED;
;             PG8_LDA(At, 1, 1); if (!fin) { PG8_STAGE(PG8_SB(1, 0), b3, voffB); PG8_STAGE(PG8_SB(1, 1), b3 + hstep, voffB); PG8_STAGE(PG8_SA(1, 0), a3, voffA); }
;             if (!fin) PG8_WAIT_V(8); PG8_WAIT_L(0); PG8_BAR; PG8_MMA(1, 0, At, B0); PG8_MMA(1, 1, At, B1); PG8_BAR; PG8_SCHED;
.LBB0_1164:
	s_waitcnt lgkmcnt(0)
	s_barrier
	v_mfma_f32_16x16x32_f16 v[62:65], v[158:161], v[186:189], v[62:65]
	s_setprio 1
	v_mfma_f32_16x16x32_f16 v[62:65], v[162:165], v[190:193], v[62:65]
	v_mfma_f32_16x16x32_f16 v[58:61], v[166:169], v[186:189], v[58:61]
	v_mfma_f32_16x16x32_f16 v[58:61], v[170:173], v[190:193], v[58:61]
	v_mfma_f32_16x16x32_f16 v[46:49], v[158:161], v[178:181], v[46:49]
	v_mfma_f32_16x16x32_f16 v[46:49], v[162:165], v[182:185], v[46:49]
	v_mfma_f32_16x16x32_f16 v[42:45], v[166:169], v[178:181], v[42:45]
	v_mfma_f32_16x16x32_f16 v[42:45], v[170:173], v[182:185], v[42:45]
	v_mfma_f32_16x16x32_f16 v[30:33], v[158:161], v[122:125], v[30:33]
	v_mfma_f32_16x16x32_f16 v[30:33], v[162:165], v[174:177], v[30:33]
	v_mfma_f32_16x16x32_f16 v[26:29], v[166:169], v[122:125], v[26:29]
	v_mfma_f32_16x16x32_f16 v[26:29], v[170:173], v[174:177], v[26:29]
	v_mfma_f32_16x16x32_f16 v[14:17], v[158:161], v[114:117], v[14:17]
	v_mfma_f32_16x16x32_f16 v[14:17], v[162:165], v[118:121], v[14:17]
	v_mfma_f32_16x16x32_f16 v[10:13], v[166:169], v[114:117], v[10:13]
	v_mfma_f32_16x16x32_f16 v[10:13], v[170:173], v[118:121], v[10:13]
	v_mfma_f32_16x16x32_f16 v[54:57], v[130:133], v[186:189], v[54:57]
	v_mfma_f32_16x16x32_f16 v[54:57], v[146:149], v[190:193], v[54:57]
	v_mfma_f32_16x16x32_f16 v[50:53], v[150:153], v[186:189], v[50:53]
	v_mfma_f32_16x16x32_f16 v[50:53], v[154:157], v[190:193], v[50:53]
	v_mfma_f32_16x16x32_f16 v[38:41], v[130:133], v[178:181], v[38:41]
	v_mfma_f32_16x16x32_f16 v[38:41], v[146:149], v[182:185], v[38:41]
	v_mfma_f32_16x16x32_f16 v[34:37], v[150:153], v[178:181], v[34:37]
	v_mfma_f32_16x16x32_f16 v[34:37], v[154:157], v[182:185], v[34:37]
	v_mfma_f32_16x16x32_f16 v[22:25], v[130:133], v[122:125], v[22:25]
	v_mfma_f32_16x16x32_f16 v[22:25], v[146:149], v[174:177], v[22:25]
	v_mfma_f32_16x16x32_f16 v[18:21], v[150:153], v[122:125], v[18:21]
	v_mfma_f32_16x16x32_f16 v[18:21], v[154:157], v[174:177], v[18:21]
	v_mfma_f32_16x16x32_f16 v[6:9], v[130:133], v[114:117], v[6:9]
	v_mfma_f32_16x16x32_f16 v[6:9], v[146:149], v[118:121], v[6:9]
	v_mfma_f32_16x16x32_f16 v[2:5], v[150:153], v[114:117], v[2:5]
	v_mfma_f32_16x16x32_f16 v[2:5], v[154:157], v[118:121], v[2:5]
	s_barrier
	s_setprio 0
	s_add_i32 s58, s58, 2
	s_add_u32 s54, s54, 0x100
	s_addc_u32 s55, s55, 0
	s_cmp_gt_u32 s58, 13
	s_cbranch_scc1 .LBB0_1175

; #define PG8_STAGE(bufoff, gbase, voff) do { if constexpr (ABL & 1) break; glds16s<(bufoff)>((voff)[0], (const void*)(gbase), ldsbw); glds16s<(bufoff) + 8192>((voff)[1], (const void*)(gbase), ldsbw); } while (0)
; #define PG8_LDA(dst, b, h) do { if constexpr (ABL & 4) break; _Pragma("unroll") for (int m = 0; m < 4; ++m) _Pragma("unroll") for (int k = 0; k < 2; ++k) dst[m][k] = *(const LAS f16x8*)(lds + PG8_SA(b, h) + aoff + m * 2048 + k * 1024); } while (0)
; #define PG8_LDB(dst, b, h) do { if constexpr (ABL & 4) break; _Pragma("unroll") for (int n = 0; n < 2; ++n) _Pragma("unroll") for (int k = 0; k < 2; ++k) dst[n][k] = *(const LAS f16x8*)(lds + PG8_SB(b, h) + boff + n * 2048 + k * 1024); } while (0)
; #define PG8_MMA(ai, bj, At, Bt) do { if constexpr (ABL & 2) break; __builtin_amdgcn_s_setprio(1); _Pragma("unroll") for (int m = 0; m < 4; ++m) _Pragma("unroll") for (int n = 0; n < 2; ++n) _Pragma("unroll") for (int k = 0; k < 2; ++k) \
;         acc[ai][bj][m][n] = __builtin_amdgcn_mfma_f32_16x16x32_f16(Bt[n][k], At[m][k], acc[ai][bj][m][n], 0, 0, 0); __builtin_amdgcn_s_setprio(0); } while (0)
; #define PG8_MMAF(ai, bj, At, Bt) do { if (t == 0) PG8_MMA0(ai, bj, At, Bt); else PG8_MMA(ai, bj, At, Bt); } while (0)
; #define PG8_WAIT_V(n) asm volatile("s_waitcnt vmcnt(" #n ")" ::: "memory")
; #define PG8_WAIT_L(n) asm volatile("s_waitcnt lgkmcnt(" #n ")" ::: "memory")
; #define PG8_BAR __builtin_amdgcn_s_barrier()
; #define PG8_SCHED __builtin_amdgcn_sched_barrier(0)
;     ...
;             if (!fin) PG8_WAIT_V(8); else PG8_WAIT_V(2); PG8_WAIT_L(0); PG8_BAR; PG8_MMAF(1, 0, At, B0); PG8_MMAF(1, 1, At, B1); PG8_BAR; PG8_SCHED;
;             PG8_LDB(B0, 1, 0); PG8_LDB(B1, 1, 1); PG8_SCHED; PG8_LDA(At, 1, 0); if (!fin) PG8_STAGE(PG8_SA(0, 1), a2 + hstep, voffA);
;             if (!fin) PG8_WAIT_V(8); else PG8_WAIT_V(0); PG8_WAIT_L(0); PG8_BAR; PG8_MMA(0, 0, At, B0); PG8_MMA(0, 1, At, B1); PG8_BAR; PG8_SCHED;
.LBB0_1169:
	s_waitcnt lgkmcnt(0)
	s_xor_b64 s[26:27], s[6:7], -1
	s_barrier
	v_mfma_f32_16x16x32_f16 v[62:65], v[158:161], v[186:189], v[62:65]
	s_setprio 1
	v_mfma_f32_16x16x32_f16 v[62:65], v[162:165], v[190:193], v[62:65]
	v_mfma_f32_16x16x32_f16 v[58:61], v[166:169], v[186:189], v[58:61]
	v_mfma_f32_16x16x32_f16 v[58:61], v[170:173], v[190:193], v[58:61]
	v_mfma_f32_16x16x32_f16 v[46:49], v[158:161], v[178:181], v[46:49]
	v_mfma_f32_16x16x32_f16 v[46:49], v[162:165], v[182:185], v[46:49]
	v_mfma_f32_16x16x32_f16 v[42:45], v[166:169], v[178:181], v[42:45]
	v_mfma_f32_16x16x32_f16 v[42:45], v[170:173], v[182:185], v[42:45]
	v_mfma_f32_16x16x32_f16 v[30:33], v[158:161], v[142:145], v[30:33]
	v_mfma_f32_16x16x32_f16 v[30:33], v[162:165], v[174:177], v[30:33]
	v_mfma_f32_16x16x32_f16 v[26:29], v[166:169], v[142:145], v[26:29]
	v_mfma_f32_16x16x32_f16 v[26:29], v[170:173], v[174:177], v[26:29]
	v_mfma_f32_16x16x32_f16 v[14:17], v[158:161], v[134:137], v[14:17]
	v_mfma_f32_16x16x32_f16 v[14:17], v[162:165], v[138:141], v[14:17]
	v_mfma_f32_16x16x32_f16 v[10:13], v[166:169], v[134:137], v[10:13]
	v_mfma_f32_16x16x32_f16 v[10:13], v[170:173], v[138:141], v[10:13]
	v_mfma_f32_16x16x32_f16 v[54:57], v[130:133], v[186:189], v[54:57]
	v_mfma_f32_16x16x32_f16 v[54:57], v[146:149], v[190:193], v[54:57]
	v_mfma_f32_16x16x32_f16 v[50:53], v[150:153], v[186:189], v[50:53]
	v_mfma_f32_16x16x32_f16 v[50:53], v[154:157], v[190:193], v[50:53]
	v_mfma_f32_16x16x32_f16 v[38:41], v[130:133], v[178:181], v[38:41]
	v_mfma_f32_16x16x32_f16 v[38:41], v[146:149], v[182:185], v[38:41]
	v_mfma_f32_16x16x32_f16 v[34:37], v[150:153], v[178:181], v[34:37]
	v_mfma_f32_16x16x32_f16 v[34:37], v[154:157], v[182:185], v[34:37]
	v_mfma_f32_16x16x32_f16 v[22:25], v[130:133], v[142:145], v[22:25]
	v_mfma_f32_16x16x32_f16 v[22:25], v[146:149], v[174:177], v[22:25]
	v_mfma_f32_16x16x32_f16 v[18:21], v[150:153], v[142:145], v[18:21]
	v_mfma_f32_16x16x32_f16 v[18:21], v[154:157], v[174:177], v[18:21]
	v_mfma_f32_16x16x32_f16 v[6:9], v[130:133], v[134:137], v[6:9]
	v_mfma_f32_16x16x32_f16 v[6:9], v[146:149], v[138:141], v[6:9]
	v_mfma_f32_16x16x32_f16 v[2:5], v[150:153], v[134:137], v[2:5]
	v_mfma_f32_16x16x32_f16 v[2:5], v[154:157], v[138:141], v[2:5]
	s_barrier
	s_setprio 0
	ds_read_b128 v[158:161], v216
	ds_read_b128 v[162:165], v216 offset:1024
	ds_read_b128 v[166:169], v216 offset:2048
	ds_read_b128 v[170:173], v216 offset:3072
	ds_read_b128 v[130:133], v217
	ds_read_b128 v[146:149], v217 offset:1024
	ds_read_b128 v[150:153], v217 offset:2048
	ds_read_b128 v[154:157], v217 offset:3072
	ds_read_b128 v[198:201], v215 offset:32768
	ds_read_b128 v[202:205], v215 offset:33792
	ds_read_b128 v[190:193], v215 offset:34816
	ds_read_b128 v[194:197], v215 offset:35840
	ds_read_b128 v[182:185], v215 offset:36864
	ds_read_b128 v[186:189], v215 offset:37888
	ds_read_b128 v[174:177], v215 offset:38912
	ds_read_b128 v[178:181], v215 offset:39936
	v_cndmask_b32_e64 v134, 0, 1, s[26:27]
	v_cmp_ne_u32_e64 s[6:7], 1, v134
	s_andn2_b64 vcc, exec, s[26:27]
	s_mov_b64 s[26:27], -1
	s_cbranch_vccnz .LBB0_1171
	s_add_u32 s26, s24, 0x40000
	s_addc_u32 s27, s25, 0
	s_add_u32 m0, s35, 0x4000
	s_nop 0
	global_load_lds_dwordx4 v1, s[26:27]
	s_nop 0
	s_add_u32 m0, s35, 0x6000
	s_nop 0
	global_load_lds_dwordx4 v211, s[26:27]
	s_waitcnt vmcnt(8)
	s_mov_b64 s[26:27], 0
